# attention: waves whose query rows all follow the key tile run the unmasked tile body in diagonal tiles (wave-uniform test)
# speedup vs baseline: 1.0191x; 1.0020x over previous
.LBB0_800:
	s_or_b64 exec, exec, s[6:7]
	s_add_i32 s0, s87, 6
	v_min_u32_e32 v36, s0, v166
	v_lshl_add_u32 v73, v36, 6, v201
	v_add_u32_e32 v36, v73, v122
	v_add_u32_e32 v38, v73, v126
	v_max_i32_e32 v172, 0, v36
	v_max_i32_e32 v38, 0, v38
	v_lshl_add_u64 v[36:37], v[134:135], 0, v[172:173]
	v_lshlrev_b32_e32 v172, 1, v38
	v_add_u32_e32 v73, v73, v154
	v_lshlrev_b64 v[36:37], 11, v[36:37]
	v_lshl_add_u64 v[40:41], v[144:145], 0, v[172:173]
	v_max_i32_e32 v172, 0, v73
	v_lshl_add_u64 v[36:37], v[146:147], 0, v[36:37]
	v_lshl_add_u64 v[74:75], v[172:173], 2, v[140:141]
	s_waitcnt lgkmcnt(0)
	s_barrier
	global_load_dwordx4 v[36:39], v[36:37], off
	s_nop 0
	global_load_dwordx4 v[40:43], v[40:41], off
	s_add_i32 s0, s87, 3
	global_load_dword v131, v[74:75], off
	s_cmp_eq_u32 s87, 0
	s_cselect_b64 s[10:11], -1, 0
	v_cmp_ge_u32_e64 s[6:7], s0, v165
	v_cmp_lt_u32_e64 s[8:9], s0, v165
	s_or_b64 s[10:11], s[10:11], s[6:7]
	s_and_saveexec_b64 s[12:13], s[10:11]
	s_xor_b64 s[56:57], exec, s[12:13]
	s_cbranch_execz .LBB0_806
	s_and_saveexec_b64 s[10:11], s[6:7]
	v_add_u32_e32 v73, s84, v168
	v_add_u32_e32 v73, 0xfffff8c0, v73
	v_cmp_ge_i32_e64 s[6:7], s93, v73
	s_andn2_b64 s[8:9], s[8:9], exec
	s_and_b64 s[6:7], s[6:7], exec
	s_or_b64 s[8:9], s[8:9], s[6:7]
	s_or_b64 exec, exec, s[10:11]
	s_and_saveexec_b64 s[64:65], s[8:9]
	s_cbranch_execz .LBB0_805
	s_cmp_eq_u32 s87, 0
	s_cbranch_scc1 .Lattn_band1
	s_add_i32 s101, s87, 3
	v_readfirstlane_b32 s100, v165
	s_sub_i32 s100, s101, s100
	s_lshl_b32 s100, s100, 6
	s_add_i32 s100, s100, 63
	v_readfirstlane_b32 s101, v192
	s_lshr_b32 s101, s101, 6
	s_lshl_b32 s101, s101, 5
	s_cmp_le_i32 s100, s101
	s_cbranch_scc0 .Lattn_band1
	s_mov_b64 s[6:7], exec
	s_branch .Lattn_nb1
.Lattn_band1:
	v_lshlrev_b32_e32 v73, 1, v159
	v_lshlrev_b32_e32 v74, 1, v157
	v_lshl_add_u32 v108, v158, 2, v72
	v_add3_u32 v171, v72, v73, v74
	ds_read_b128 v[72:75], v171
	ds_read_b128 v[76:79], v171 offset:64
	ds_read_b128 v[80:83], v108 offset:18432
	ds_read_b128 v[84:87], v171 offset:2304
	ds_read_b128 v[88:91], v171 offset:2368
	ds_read_b128 v[92:95], v108 offset:18496
	ds_read_b128 v[96:99], v171 offset:4608
	ds_read_b128 v[100:103], v171 offset:4672
	ds_read_b128 v[104:107], v108 offset:18560
	ds_read_b128 v[150:153], v171 offset:6912
	ds_read_b128 v[188:191], v171 offset:6976
	ds_read_b128 v[204:207], v108 offset:18624
	s_waitcnt lgkmcnt(9)
	v_mfma_f32_16x16x32_bf16 v[108:111], v[72:75], v[20:23], v[80:83]
	s_add_i32 s6, s84, 0xc0
	s_cmpk_lt_u32 s6, 0xf0
	s_cselect_b64 s[72:73], -1, 0
	v_mfma_f32_16x16x32_bf16 v[208:211], v[76:79], v[24:27], v[108:111]
	s_waitcnt lgkmcnt(6)
	v_mfma_f32_16x16x32_bf16 v[108:111], v[84:87], v[20:23], v[92:95]
	v_mfma_f32_16x16x32_bf16 v[72:75], v[72:75], v[28:31], v[80:83]
	v_mfma_f32_16x16x32_bf16 v[212:215], v[88:91], v[24:27], v[108:111]
	s_waitcnt lgkmcnt(3)
	v_mfma_f32_16x16x32_bf16 v[108:111], v[96:99], v[20:23], v[104:107]
	v_mfma_f32_16x16x32_bf16 v[116:119], v[76:79], v[32:35], v[72:75]
	v_mfma_f32_16x16x32_bf16 v[72:75], v[84:87], v[28:31], v[92:95]
	v_mfma_f32_16x16x32_bf16 v[216:219], v[100:103], v[24:27], v[108:111]
	s_waitcnt lgkmcnt(0)
	v_mfma_f32_16x16x32_bf16 v[108:111], v[150:153], v[20:23], v[204:207]
	v_mfma_f32_16x16x32_bf16 v[112:115], v[88:91], v[32:35], v[72:75]
	v_mfma_f32_16x16x32_bf16 v[72:75], v[96:99], v[28:31], v[104:107]
	v_mfma_f32_16x16x32_bf16 v[220:223], v[188:191], v[24:27], v[108:111]
	v_mfma_f32_16x16x32_bf16 v[108:111], v[100:103], v[32:35], v[72:75]
	v_mfma_f32_16x16x32_bf16 v[72:75], v[150:153], v[28:31], v[204:207]
	v_add_u32_e32 v150, s84, v158
	v_add_u32_e32 v172, 0xc0, v150
	v_cmp_gt_i32_e64 s[6:7], v172, v133
	s_or_b64 s[8:9], s[72:73], s[6:7]
	v_cndmask_b32_e64 v151, v208, v202, s[8:9]
	v_cmp_ge_i32_e64 s[8:9], v172, v133
	s_or_b64 s[8:9], s[72:73], s[8:9]
	v_add_u32_e32 v203, 0xc2, v150
	v_cndmask_b32_e64 v152, v209, v202, s[8:9]
	v_cmp_gt_i32_e64 s[8:9], v203, v133
	s_or_b64 s[8:9], s[72:73], s[8:9]
	v_add_u32_e32 v224, 0xc3, v150
	v_cndmask_b32_e64 v153, v210, v202, s[8:9]
	v_cmp_gt_i32_e64 s[8:9], v224, v133
	v_mfma_f32_16x16x32_bf16 v[104:107], v[188:191], v[32:35], v[72:75]
	s_or_b64 s[8:9], s[72:73], s[8:9]
	v_cndmask_b32_e64 v177, v211, v202, s[8:9]
	s_nop 0
	v_add_u32_e32 v72, v171, v162
	v_add_u32_e32 v171, 0xd0, v150
	v_cmp_gt_u32_e64 s[8:9], s50, v171
	v_cmp_gt_i32_e64 s[10:11], v171, v133
	s_or_b64 s[10:11], s[8:9], s[10:11]
	v_max_f32_e32 v171, v151, v151
	v_cndmask_b32_e64 v180, v212, v202, s[10:11]
	v_add_u32_e32 v212, 0xd1, v150
	v_cmp_gt_u32_e64 s[10:11], s50, v212
	v_cmp_gt_i32_e64 s[12:13], v212, v133
	s_or_b64 s[12:13], s[10:11], s[12:13]
	s_or_b64 s[6:7], s[8:9], s[6:7]
	v_cndmask_b32_e64 v181, v213, v202, s[12:13]
	v_add_u32_e32 v213, 0xd2, v150
	v_cmp_gt_u32_e64 s[12:13], s50, v213
	v_cmp_gt_i32_e64 s[14:15], v213, v133
	s_or_b64 s[14:15], s[12:13], s[14:15]
	v_cndmask_b32_e64 v112, v112, v202, s[6:7]
	v_cndmask_b32_e64 v182, v214, v202, s[14:15]
	v_add_u32_e32 v214, 0xd3, v150
	v_cmp_gt_u32_e64 s[14:15], s50, v214
	v_cmp_gt_i32_e64 s[16:17], v214, v133
	s_or_b64 s[16:17], s[14:15], s[16:17]
	v_cmp_gt_i32_e64 s[6:7], v212, v143
	v_cndmask_b32_e64 v183, v215, v202, s[16:17]
	v_add_u32_e32 v215, 0xe0, v150
	v_cmp_gt_u32_e64 s[16:17], s50, v215
	v_cmp_gt_i32_e64 s[18:19], v215, v133
	s_or_b64 s[18:19], s[16:17], s[18:19]
	s_or_b64 s[6:7], s[10:11], s[6:7]
	v_cndmask_b32_e64 v188, v216, v202, s[18:19]
	v_add_u32_e32 v216, 0xe1, v150
	v_cmp_gt_u32_e64 s[18:19], s50, v216
	v_cmp_gt_i32_e64 s[20:21], v216, v133
	s_or_b64 s[20:21], s[18:19], s[20:21]
	v_cndmask_b32_e64 v113, v113, v202, s[6:7]
	v_cndmask_b32_e64 v189, v217, v202, s[20:21]
	v_add_u32_e32 v217, 0xe2, v150
	v_cmp_gt_u32_e64 s[20:21], s50, v217
	v_cmp_gt_i32_e64 s[22:23], v217, v133
	s_or_b64 s[22:23], s[20:21], s[22:23]
	v_cmp_gt_i32_e64 s[6:7], v213, v143
	v_cndmask_b32_e64 v190, v218, v202, s[22:23]
	v_add_u32_e32 v218, 0xe3, v150
	v_cmp_gt_u32_e64 s[22:23], s50, v218
	v_cmp_gt_i32_e64 s[24:25], v218, v133
	s_or_b64 s[24:25], s[22:23], s[24:25]
	s_or_b64 s[6:7], s[12:13], s[6:7]
	v_cndmask_b32_e64 v191, v219, v202, s[24:25]
	v_add_co_u32_e64 v219, s[24:25], s50, v150
	v_cmp_gt_i32_e64 s[26:27], v219, v133
	s_or_b64 s[26:27], s[24:25], s[26:27]
	v_cndmask_b32_e64 v114, v114, v202, s[6:7]
	v_cndmask_b32_e64 v208, v220, v202, s[26:27]
	v_add_u32_e32 v220, 0xf1, v150
	v_cmp_gt_u32_e64 s[26:27], s50, v220
	v_cmp_gt_i32_e64 s[28:29], v220, v133
	s_or_b64 s[28:29], s[26:27], s[28:29]
	v_cmp_gt_i32_e64 s[6:7], v214, v143
	v_cndmask_b32_e64 v209, v221, v202, s[28:29]
	v_add_u32_e32 v221, 0xf2, v150
	v_cmp_gt_u32_e64 s[28:29], s50, v221
	v_cmp_gt_i32_e64 s[30:31], v221, v133
	s_or_b64 s[30:31], s[28:29], s[30:31]
	s_or_b64 s[6:7], s[14:15], s[6:7]
	v_cndmask_b32_e64 v210, v222, v202, s[30:31]
	v_add_u32_e32 v222, 0xf3, v150
	v_max_f32_e32 v150, v152, v152
	v_max_f32_e32 v150, v171, v150
	v_max3_f32 v150, v150, v153, v177
	v_max3_f32 v150, v150, v180, v181
	v_max3_f32 v150, v150, v182, v183
	v_cmp_gt_u32_e64 s[30:31], s50, v222
	v_cmp_gt_i32_e64 s[36:37], v222, v133
	v_max3_f32 v150, v150, v188, v189
	s_or_b64 s[36:37], s[30:31], s[36:37]
	v_max3_f32 v150, v150, v190, v191
	v_cndmask_b32_e64 v211, v223, v202, s[36:37]
	v_max3_f32 v150, v150, v208, v209
	v_max3_f32 v150, v150, v210, v211
	v_mov_b32_e32 v171, v150
	s_nop 1
	v_permlane16_swap_b32_e32 v150, v171
	v_mov_b32_e32 v171, v150
	s_nop 1
	v_permlane32_swap_b32_e32 v150, v171
	v_max_f32_e32 v150, v150, v150
	v_max_f32_e32 v171, v148, v148
	v_max_f32_e32 v171, v171, v150
	v_sub_f32_e32 v188, v188, v171
	v_sub_f32_e32 v150, v151, v171
	v_exp_f32_e32 v204, v188
	v_sub_f32_e32 v188, v189, v171
	v_exp_f32_e32 v174, v150
	v_sub_f32_e32 v150, v152, v171
	v_exp_f32_e32 v205, v188
	v_sub_f32_e32 v188, v190, v171
	v_exp_f32_e32 v175, v150
	v_sub_f32_e32 v150, v153, v171
	v_sub_f32_e32 v180, v180, v171
	v_sub_f32_e32 v181, v181, v171
	v_exp_f32_e32 v206, v188
	v_sub_f32_e32 v188, v191, v171
	v_exp_f32_e32 v176, v150
	v_sub_f32_e32 v150, v177, v171
	v_exp_f32_e32 v180, v180
	v_exp_f32_e32 v181, v181
	v_exp_f32_e32 v207, v188
	v_sub_f32_e32 v188, v208, v171
	v_exp_f32_e32 v177, v150
	v_sub_f32_e32 v182, v182, v171
	v_sub_f32_e32 v183, v183, v171
	v_exp_f32_e32 v208, v188
	v_sub_f32_e32 v188, v209, v171
	v_exp_f32_e32 v182, v182
	v_exp_f32_e32 v183, v183
	v_exp_f32_e32 v209, v188
	v_sub_f32_e32 v188, v210, v171
	v_pk_add_f32 v[150:151], v[174:175], 0 op_sel_hi:[1,0]
	v_exp_f32_e32 v210, v188
	v_sub_f32_e32 v188, v211, v171
	v_pk_add_f32 v[150:151], v[180:181], v[150:151]
	v_exp_f32_e32 v211, v188
	v_pk_add_f32 v[152:153], v[176:177], 0 op_sel_hi:[1,0]
	v_pk_add_f32 v[150:151], v[204:205], v[150:151]
	v_cndmask_b32_e64 v115, v115, v202, s[6:7]
	v_cmp_gt_i32_e64 s[6:7], v215, v143
	v_pk_add_f32 v[152:153], v[182:183], v[152:153]
	v_pk_add_f32 v[150:151], v[208:209], v[150:151]
	s_or_b64 s[6:7], s[16:17], s[6:7]
	v_pk_add_f32 v[152:153], v[206:207], v[152:153]
	v_add_f32_e32 v150, v150, v151
	v_cndmask_b32_e64 v151, v108, v202, s[6:7]
	v_cmp_gt_i32_e64 s[6:7], v216, v143
	v_pk_add_f32 v[152:153], v[210:211], v[152:153]
	s_or_b64 s[6:7], s[18:19], s[6:7]
	v_add_f32_e32 v152, v152, v153
	v_cmp_gt_i32_e64 s[36:37], v172, v143
	v_cndmask_b32_e64 v153, v109, v202, s[6:7]
	v_cmp_gt_i32_e64 s[6:7], v217, v143
	v_add_u32_e32 v73, 0x2000, v72
	s_or_b64 s[36:37], s[72:73], s[36:37]
	s_or_b64 s[6:7], s[20:21], s[6:7]
	ds_read2_b64 v[100:103], v73 offset0:128 offset1:132
	ds_read2_b64 v[96:99], v73 offset0:136 offset1:140
	v_add_u32_e32 v73, 0x2800, v72
	v_cndmask_b32_e64 v116, v116, v202, s[36:37]
	v_cmp_ge_i32_e64 s[36:37], v172, v143
	v_cndmask_b32_e64 v172, v110, v202, s[6:7]
	v_cmp_gt_i32_e64 s[6:7], v218, v143
	ds_read2_b64 v[92:95], v73 offset0:160 offset1:164
	ds_read2_b64 v[88:91], v73 offset0:168 offset1:172
	v_add_u32_e32 v73, 0x3000, v72
	v_add_u32_e32 v72, 0x3800, v72
	s_or_b64 s[6:7], s[22:23], s[6:7]
	ds_read2_b64 v[84:87], v73 offset0:192 offset1:196
	ds_read2_b64 v[80:83], v73 offset0:200 offset1:204
	ds_read2_b64 v[76:79], v72 offset0:224 offset1:228
	ds_read2_b64 v[72:75], v72 offset0:232 offset1:236
	v_cvt_pk_bf16_f32 v188, v174, v175
	s_or_b64 s[36:37], s[72:73], s[36:37]
	v_cndmask_b32_e64 v174, v111, v202, s[6:7]
	v_cmp_gt_i32_e64 s[6:7], v219, v143
	v_cndmask_b32_e64 v117, v117, v202, s[36:37]
	v_cmp_gt_i32_e64 s[36:37], v203, v143
	s_or_b64 s[6:7], s[24:25], s[6:7]
	s_or_b64 s[36:37], s[72:73], s[36:37]
	v_cndmask_b32_e64 v175, v104, v202, s[6:7]
	v_cmp_gt_i32_e64 s[6:7], v220, v143
	v_cndmask_b32_e64 v118, v118, v202, s[36:37]
	v_cmp_gt_i32_e64 s[36:37], v224, v143
	s_or_b64 s[6:7], s[26:27], s[6:7]
	v_cvt_pk_bf16_f32 v189, v176, v177
	s_or_b64 s[36:37], s[72:73], s[36:37]
	v_cndmask_b32_e64 v176, v105, v202, s[6:7]
	v_max_f32_e32 v104, v117, v117
	v_max_f32_e32 v105, v116, v116
	v_cndmask_b32_e64 v119, v119, v202, s[36:37]
	v_max_f32_e32 v104, v105, v104
	v_max3_f32 v104, v104, v118, v119
	v_cmp_gt_i32_e64 s[6:7], v221, v143
	v_max3_f32 v104, v104, v112, v113
	s_or_b64 s[6:7], s[28:29], s[6:7]
	v_max3_f32 v104, v104, v114, v115
	v_cndmask_b32_e64 v177, v106, v202, s[6:7]
	v_cmp_gt_i32_e64 s[6:7], v222, v143
	v_max3_f32 v104, v104, v151, v153
	s_or_b64 s[6:7], s[30:31], s[6:7]
	v_max3_f32 v104, v104, v172, v174
	v_cvt_pk_bf16_f32 v190, v180, v181
	v_cndmask_b32_e64 v180, v107, v202, s[6:7]
	v_max3_f32 v104, v104, v175, v176
	v_max3_f32 v104, v104, v177, v180
	v_mov_b32_e32 v105, v104
	s_nop 1
	v_permlane16_swap_b32_e32 v104, v105
	v_mov_b32_e32 v105, v104
	s_nop 1
	v_permlane32_swap_b32_e32 v104, v105
	v_max_f32_e32 v104, v104, v104
	v_max_f32_e32 v105, v149, v149
	v_cvt_pk_bf16_f32 v191, v182, v183
	v_max_f32_e32 v182, v105, v104
	v_sub_f32_e32 v104, v116, v182
	v_sub_f32_e32 v105, v117, v182
	v_sub_f32_e32 v106, v118, v182
	v_sub_f32_e32 v107, v119, v182
	v_sub_f32_e32 v116, v151, v182
	v_sub_f32_e32 v151, v175, v182
	v_exp_f32_e32 v104, v104
	v_exp_f32_e32 v105, v105
	v_exp_f32_e32 v106, v106
	v_exp_f32_e32 v107, v107
	v_sub_f32_e32 v112, v112, v182
	v_sub_f32_e32 v113, v113, v182
	v_sub_f32_e32 v114, v114, v182
	v_sub_f32_e32 v115, v115, v182
	v_sub_f32_e32 v119, v174, v182
	v_exp_f32_e32 v174, v151
	v_sub_f32_e32 v151, v176, v182
	v_exp_f32_e32 v112, v112
	v_exp_f32_e32 v113, v113
	v_exp_f32_e32 v114, v114
	v_exp_f32_e32 v115, v115
	v_sub_f32_e32 v117, v153, v182
	v_sub_f32_e32 v118, v172, v182
	v_exp_f32_e32 v175, v151
	v_sub_f32_e32 v151, v177, v182
	v_sub_f32_e32 v148, v148, v171
	v_exp_f32_e32 v116, v116
	v_exp_f32_e32 v117, v117
	v_exp_f32_e32 v118, v118
	v_exp_f32_e32 v119, v119
	v_exp_f32_e32 v176, v151
	v_sub_f32_e32 v151, v180, v182
	v_exp_f32_e32 v148, v148
	v_exp_f32_e32 v177, v151
	v_pk_add_f32 v[108:109], v[104:105], 0 op_sel_hi:[1,0]
	v_pk_add_f32 v[110:111], v[106:107], 0 op_sel_hi:[1,0]
	v_pk_add_f32 v[108:109], v[112:113], v[108:109]
	v_pk_add_f32 v[110:111], v[114:115], v[110:111]
	v_pk_add_f32 v[108:109], v[116:117], v[108:109]
	v_pk_add_f32 v[110:111], v[118:119], v[110:111]
	v_pk_mul_f32 v[70:71], v[70:71], v[148:149] op_sel_hi:[1,0]
	v_pk_mul_f32 v[68:69], v[68:69], v[148:149] op_sel_hi:[1,0]
	v_pk_mul_f32 v[66:67], v[66:67], v[148:149] op_sel_hi:[1,0]
	v_pk_mul_f32 v[64:65], v[64:65], v[148:149] op_sel_hi:[1,0]
	v_pk_mul_f32 v[62:63], v[62:63], v[148:149] op_sel_hi:[1,0]
	v_pk_mul_f32 v[60:61], v[60:61], v[148:149] op_sel_hi:[1,0]
	v_pk_mul_f32 v[18:19], v[18:19], v[148:149] op_sel_hi:[1,0]
	v_pk_mul_f32 v[16:17], v[16:17], v[148:149] op_sel_hi:[1,0]
	v_sub_f32_e32 v149, v149, v182
	v_pk_add_f32 v[110:111], v[176:177], v[110:111]
	v_pk_add_f32 v[108:109], v[174:175], v[108:109]
	v_exp_f32_e32 v149, v149
	v_pk_mov_b32 v[180:181], v[108:109], v[110:111] op_sel:[1,0]
	v_mov_b32_e32 v109, v111
	v_pk_add_f32 v[108:109], v[180:181], v[108:109]
	v_cvt_pk_bf16_f32 v204, v204, v205
	v_cvt_pk_bf16_f32 v205, v206, v207
	v_cvt_pk_bf16_f32 v206, v208, v209
	v_cvt_pk_bf16_f32 v207, v210, v211
	s_waitcnt lgkmcnt(7)
	v_mfma_f32_16x16x32_bf16 v[68:71], v[100:103], v[188:191], v[68:71]
	v_mov_b32_e32 v151, v108
	v_mov_b32_e32 v153, v109
	v_pk_add_f32 v[108:109], v[150:151], v[152:153]
	s_waitcnt lgkmcnt(5)
	v_mfma_f32_16x16x32_bf16 v[64:67], v[92:95], v[188:191], v[64:67]
	v_fma_f32 v136, v136, v148, v108
	v_fma_f32 v137, v137, v149, v109
	v_mov_b32_e32 v108, v149
	v_pk_mul_f32 v[14:15], v[14:15], v[108:109] op_sel_hi:[1,0]
	v_pk_mul_f32 v[12:13], v[12:13], v[108:109] op_sel_hi:[1,0]
	v_pk_mul_f32 v[10:11], v[10:11], v[108:109] op_sel_hi:[1,0]
	v_pk_mul_f32 v[8:9], v[8:9], v[108:109] op_sel_hi:[1,0]
	v_pk_mul_f32 v[6:7], v[6:7], v[108:109] op_sel_hi:[1,0]
	v_pk_mul_f32 v[4:5], v[4:5], v[108:109] op_sel_hi:[1,0]
	v_pk_mul_f32 v[2:3], v[2:3], v[108:109] op_sel_hi:[1,0]
	v_pk_mul_f32 v[0:1], v[0:1], v[108:109] op_sel_hi:[1,0]
	s_waitcnt lgkmcnt(3)
	v_mfma_f32_16x16x32_bf16 v[60:63], v[84:87], v[188:191], v[60:63]
	v_cvt_pk_bf16_f32 v104, v104, v105
	v_cvt_pk_bf16_f32 v105, v106, v107
	v_cvt_pk_bf16_f32 v106, v112, v113
	s_waitcnt lgkmcnt(1)
	v_mfma_f32_16x16x32_bf16 v[16:19], v[76:79], v[188:191], v[16:19]
	v_cvt_pk_bf16_f32 v107, v114, v115
	v_cvt_pk_bf16_f32 v108, v116, v117
	v_cvt_pk_bf16_f32 v109, v118, v119
	v_mfma_f32_16x16x32_bf16 v[68:71], v[96:99], v[204:207], v[68:71]
	v_cvt_pk_bf16_f32 v110, v174, v175
	v_cvt_pk_bf16_f32 v111, v176, v177
	s_mov_b32 s20, s78
	v_mfma_f32_16x16x32_bf16 v[12:15], v[100:103], v[104:107], v[12:15]
	v_mov_b32_e32 v149, v182
	v_mov_b32_e32 v148, v171
	v_mfma_f32_16x16x32_bf16 v[8:11], v[92:95], v[104:107], v[8:11]
	v_mfma_f32_16x16x32_bf16 v[4:7], v[84:87], v[104:107], v[4:7]
	v_mfma_f32_16x16x32_bf16 v[0:3], v[76:79], v[104:107], v[0:3]
	v_mfma_f32_16x16x32_bf16 v[64:67], v[88:91], v[204:207], v[64:67]
	v_mfma_f32_16x16x32_bf16 v[60:63], v[80:83], v[204:207], v[60:63]
	s_waitcnt lgkmcnt(0)
	v_mfma_f32_16x16x32_bf16 v[16:19], v[72:75], v[204:207], v[16:19]
	v_mfma_f32_16x16x32_bf16 v[12:15], v[96:99], v[108:111], v[12:15]
	v_mfma_f32_16x16x32_bf16 v[8:11], v[88:91], v[108:111], v[8:11]
	v_mfma_f32_16x16x32_bf16 v[4:7], v[80:83], v[108:111], v[4:7]
	v_mfma_f32_16x16x32_bf16 v[0:3], v[72:75], v[108:111], v[0:3]

.Lattn_nb1:
	v_lshlrev_b32_e32 v73, 1, v159
	v_lshlrev_b32_e32 v74, 1, v157
	v_lshl_add_u32 v108, v158, 2, v72
	v_add3_u32 v171, v72, v73, v74
	ds_read_b128 v[72:75], v171
	ds_read_b128 v[76:79], v171 offset:64
	ds_read_b128 v[80:83], v108 offset:18432
	ds_read_b128 v[84:87], v171 offset:2304
	ds_read_b128 v[88:91], v171 offset:2368
	ds_read_b128 v[92:95], v108 offset:18496
	ds_read_b128 v[96:99], v171 offset:4608
	ds_read_b128 v[100:103], v171 offset:4672
	ds_read_b128 v[104:107], v108 offset:18560
	ds_read_b128 v[150:153], v171 offset:6912
	ds_read_b128 v[188:191], v171 offset:6976
	ds_read_b128 v[204:207], v108 offset:18624
	s_waitcnt lgkmcnt(9)
	v_mfma_f32_16x16x32_bf16 v[108:111], v[72:75], v[20:23], v[80:83]
	v_mfma_f32_16x16x32_bf16 v[208:211], v[76:79], v[24:27], v[108:111]
	s_waitcnt lgkmcnt(6)
	v_mfma_f32_16x16x32_bf16 v[108:111], v[84:87], v[20:23], v[92:95]
	v_mfma_f32_16x16x32_bf16 v[72:75], v[72:75], v[28:31], v[80:83]
	v_mfma_f32_16x16x32_bf16 v[212:215], v[88:91], v[24:27], v[108:111]
	s_waitcnt lgkmcnt(3)
	v_mfma_f32_16x16x32_bf16 v[108:111], v[96:99], v[20:23], v[104:107]
	v_mfma_f32_16x16x32_bf16 v[116:119], v[76:79], v[32:35], v[72:75]
	v_mfma_f32_16x16x32_bf16 v[72:75], v[84:87], v[28:31], v[92:95]
	v_mfma_f32_16x16x32_bf16 v[216:219], v[100:103], v[24:27], v[108:111]
	s_waitcnt lgkmcnt(0)
	v_mfma_f32_16x16x32_bf16 v[108:111], v[150:153], v[20:23], v[204:207]
	v_mfma_f32_16x16x32_bf16 v[112:115], v[88:91], v[32:35], v[72:75]
	v_mfma_f32_16x16x32_bf16 v[72:75], v[96:99], v[28:31], v[104:107]
	v_mfma_f32_16x16x32_bf16 v[220:223], v[188:191], v[24:27], v[108:111]
	v_mfma_f32_16x16x32_bf16 v[108:111], v[100:103], v[32:35], v[72:75]
	v_mfma_f32_16x16x32_bf16 v[72:75], v[150:153], v[28:31], v[204:207]
	v_max_f32_e32 v150, v209, v209
	v_max_f32_e32 v151, v208, v208
	v_max_f32_e32 v150, v151, v150
	v_max3_f32 v150, v150, v210, v211
	v_max3_f32 v150, v150, v212, v213
	v_max3_f32 v150, v150, v214, v215
	v_max3_f32 v150, v150, v216, v217
	v_max3_f32 v150, v150, v218, v219
	v_max3_f32 v150, v150, v220, v221
	v_max3_f32 v150, v150, v222, v223
	v_mov_b32_e32 v151, v150
	s_nop 1
	v_permlane16_swap_b32_e32 v150, v151
	v_mov_b32_e32 v151, v150
	s_nop 1
	v_permlane32_swap_b32_e32 v150, v151
	v_max_f32_e32 v150, v150, v150
	v_max_f32_e32 v151, v148, v148
	v_mfma_f32_16x16x32_bf16 v[104:107], v[188:191], v[32:35], v[72:75]
	s_nop 2
	v_add_u32_e32 v72, v171, v162
	v_max_f32_e32 v171, v151, v150
	v_sub_f32_e32 v172, v212, v171
	v_exp_f32_e32 v180, v172
	v_sub_f32_e32 v172, v213, v171
	v_exp_f32_e32 v181, v172
	v_sub_f32_e32 v172, v214, v171
	v_exp_f32_e32 v182, v172
	v_sub_f32_e32 v172, v215, v171
	v_exp_f32_e32 v183, v172
	v_sub_f32_e32 v172, v216, v171
	v_sub_f32_e32 v150, v208, v171
	v_exp_f32_e32 v204, v172
	v_sub_f32_e32 v172, v217, v171
	v_exp_f32_e32 v174, v150
	v_sub_f32_e32 v150, v209, v171
	v_exp_f32_e32 v205, v172
	v_sub_f32_e32 v172, v218, v171
	v_exp_f32_e32 v175, v150
	v_sub_f32_e32 v150, v210, v171
	v_exp_f32_e32 v206, v172
	v_sub_f32_e32 v172, v219, v171
	v_exp_f32_e32 v176, v150
	v_sub_f32_e32 v150, v211, v171
	v_exp_f32_e32 v207, v172
	v_sub_f32_e32 v172, v220, v171
	v_exp_f32_e32 v177, v150
	v_exp_f32_e32 v208, v172
	v_sub_f32_e32 v172, v221, v171
	v_exp_f32_e32 v209, v172
	v_sub_f32_e32 v172, v222, v171
	v_exp_f32_e32 v210, v172
	v_sub_f32_e32 v172, v223, v171
	v_exp_f32_e32 v211, v172
	v_pk_add_f32 v[150:151], v[174:175], 0 op_sel_hi:[1,0]
	v_pk_add_f32 v[152:153], v[176:177], 0 op_sel_hi:[1,0]
	v_pk_add_f32 v[150:151], v[180:181], v[150:151]
	v_pk_add_f32 v[152:153], v[182:183], v[152:153]
	v_pk_add_f32 v[150:151], v[204:205], v[150:151]
	v_pk_add_f32 v[152:153], v[206:207], v[152:153]
	v_pk_add_f32 v[150:151], v[208:209], v[150:151]
	v_pk_add_f32 v[152:153], v[210:211], v[152:153]
	v_add_f32_e32 v150, v150, v151
	v_add_f32_e32 v152, v152, v153
	v_max_f32_e32 v151, v117, v117
	v_max_f32_e32 v153, v116, v116
	v_max_f32_e32 v151, v153, v151
	v_max3_f32 v151, v151, v118, v119
	v_max3_f32 v151, v151, v112, v113
	v_max3_f32 v151, v151, v114, v115
	v_max3_f32 v151, v151, v108, v109
	v_max3_f32 v151, v151, v110, v111
	v_max3_f32 v151, v151, v104, v105
	v_max3_f32 v151, v151, v106, v107
	v_mov_b32_e32 v153, v151
	s_nop 1
	v_permlane16_swap_b32_e32 v151, v153
	v_mov_b32_e32 v153, v151
	s_nop 1
	v_permlane32_swap_b32_e32 v151, v153
	v_add_u32_e32 v73, 0x2000, v72
	v_max_f32_e32 v151, v151, v151
	v_max_f32_e32 v153, v149, v149
	ds_read2_b64 v[100:103], v73 offset0:128 offset1:132
	ds_read2_b64 v[96:99], v73 offset0:136 offset1:140
	v_add_u32_e32 v73, 0x2800, v72
	v_max_f32_e32 v172, v153, v151
	ds_read2_b64 v[92:95], v73 offset0:160 offset1:164
	ds_read2_b64 v[88:91], v73 offset0:168 offset1:172
	v_add_u32_e32 v73, 0x3000, v72
	v_add_u32_e32 v72, 0x3800, v72
	v_sub_f32_e32 v116, v116, v172
	v_sub_f32_e32 v117, v117, v172
	v_sub_f32_e32 v118, v118, v172
	v_sub_f32_e32 v119, v119, v172
	v_sub_f32_e32 v104, v104, v172
	ds_read2_b64 v[84:87], v73 offset0:192 offset1:196
	ds_read2_b64 v[80:83], v73 offset0:200 offset1:204
	ds_read2_b64 v[76:79], v72 offset0:224 offset1:228
	ds_read2_b64 v[72:75], v72 offset0:232 offset1:236
	v_cvt_pk_bf16_f32 v188, v174, v175
	v_cvt_pk_bf16_f32 v189, v176, v177
	v_cvt_pk_bf16_f32 v190, v180, v181
	v_exp_f32_e32 v116, v116
	v_exp_f32_e32 v117, v117
	v_exp_f32_e32 v118, v118
	v_exp_f32_e32 v119, v119
	v_sub_f32_e32 v112, v112, v172
	v_sub_f32_e32 v113, v113, v172
	v_sub_f32_e32 v114, v114, v172
	v_sub_f32_e32 v115, v115, v172
	v_exp_f32_e32 v180, v104
	v_sub_f32_e32 v104, v105, v172
	v_exp_f32_e32 v112, v112
	v_exp_f32_e32 v113, v113
	v_exp_f32_e32 v114, v114
	v_exp_f32_e32 v115, v115
	v_sub_f32_e32 v108, v108, v172
	v_sub_f32_e32 v109, v109, v172
	v_sub_f32_e32 v110, v110, v172
	v_sub_f32_e32 v111, v111, v172
	v_exp_f32_e32 v181, v104
	v_sub_f32_e32 v104, v106, v172
	v_sub_f32_e32 v148, v148, v171
	v_cvt_pk_bf16_f32 v191, v182, v183
	v_exp_f32_e32 v108, v108
	v_exp_f32_e32 v109, v109
	v_exp_f32_e32 v110, v110
	v_exp_f32_e32 v111, v111
	v_exp_f32_e32 v182, v104
	v_sub_f32_e32 v104, v107, v172
	v_exp_f32_e32 v148, v148
	v_exp_f32_e32 v183, v104
	v_pk_add_f32 v[174:175], v[116:117], 0 op_sel_hi:[1,0]
	v_pk_add_f32 v[176:177], v[118:119], 0 op_sel_hi:[1,0]
	v_pk_add_f32 v[174:175], v[112:113], v[174:175]
	v_pk_add_f32 v[176:177], v[114:115], v[176:177]
	v_pk_add_f32 v[174:175], v[108:109], v[174:175]
	v_pk_add_f32 v[176:177], v[110:111], v[176:177]
	v_pk_mul_f32 v[70:71], v[70:71], v[148:149] op_sel_hi:[1,0]
	v_pk_mul_f32 v[68:69], v[68:69], v[148:149] op_sel_hi:[1,0]
	v_pk_mul_f32 v[66:67], v[66:67], v[148:149] op_sel_hi:[1,0]
	v_pk_mul_f32 v[64:65], v[64:65], v[148:149] op_sel_hi:[1,0]
	v_pk_mul_f32 v[62:63], v[62:63], v[148:149] op_sel_hi:[1,0]
	v_pk_mul_f32 v[60:61], v[60:61], v[148:149] op_sel_hi:[1,0]
	v_pk_mul_f32 v[18:19], v[18:19], v[148:149] op_sel_hi:[1,0]
	v_pk_mul_f32 v[16:17], v[16:17], v[148:149] op_sel_hi:[1,0]
	v_sub_f32_e32 v149, v149, v172
	v_pk_add_f32 v[104:105], v[182:183], v[176:177]
	v_pk_add_f32 v[106:107], v[180:181], v[174:175]
	v_exp_f32_e32 v149, v149
	v_pk_mov_b32 v[174:175], v[106:107], v[104:105] op_sel:[1,0]
	v_mov_b32_e32 v107, v105
	v_pk_add_f32 v[104:105], v[174:175], v[106:107]
	v_cvt_pk_bf16_f32 v204, v204, v205
	v_cvt_pk_bf16_f32 v205, v206, v207
	v_cvt_pk_bf16_f32 v206, v208, v209
	v_cvt_pk_bf16_f32 v207, v210, v211
	s_waitcnt lgkmcnt(7)
	v_mfma_f32_16x16x32_bf16 v[68:71], v[100:103], v[188:191], v[68:71]
	v_mov_b32_e32 v151, v104
	v_mov_b32_e32 v153, v105
	v_pk_add_f32 v[104:105], v[150:151], v[152:153]
	s_waitcnt lgkmcnt(5)
	v_mfma_f32_16x16x32_bf16 v[64:67], v[92:95], v[188:191], v[64:67]
	v_fma_f32 v136, v136, v148, v104
	v_fma_f32 v137, v137, v149, v105
	v_mov_b32_e32 v104, v149
	v_pk_mul_f32 v[14:15], v[14:15], v[104:105] op_sel_hi:[1,0]
	v_pk_mul_f32 v[12:13], v[12:13], v[104:105] op_sel_hi:[1,0]
	v_pk_mul_f32 v[10:11], v[10:11], v[104:105] op_sel_hi:[1,0]
	v_pk_mul_f32 v[8:9], v[8:9], v[104:105] op_sel_hi:[1,0]
	v_pk_mul_f32 v[6:7], v[6:7], v[104:105] op_sel_hi:[1,0]
	v_pk_mul_f32 v[4:5], v[4:5], v[104:105] op_sel_hi:[1,0]
	v_pk_mul_f32 v[2:3], v[2:3], v[104:105] op_sel_hi:[1,0]
	v_pk_mul_f32 v[0:1], v[0:1], v[104:105] op_sel_hi:[1,0]
	s_waitcnt lgkmcnt(3)
	v_mfma_f32_16x16x32_bf16 v[60:63], v[84:87], v[188:191], v[60:63]
	v_cvt_pk_bf16_f32 v104, v116, v117
	v_cvt_pk_bf16_f32 v105, v118, v119
	v_cvt_pk_bf16_f32 v106, v112, v113
	s_waitcnt lgkmcnt(1)
	v_mfma_f32_16x16x32_bf16 v[16:19], v[76:79], v[188:191], v[16:19]
	v_cvt_pk_bf16_f32 v107, v114, v115
	v_cvt_pk_bf16_f32 v108, v108, v109
	v_cvt_pk_bf16_f32 v109, v110, v111
	v_mfma_f32_16x16x32_bf16 v[68:71], v[96:99], v[204:207], v[68:71]
	v_cvt_pk_bf16_f32 v110, v180, v181
	v_cvt_pk_bf16_f32 v111, v182, v183
	v_mov_b32_e32 v148, v171
	v_mfma_f32_16x16x32_bf16 v[12:15], v[100:103], v[104:107], v[12:15]
	v_mov_b32_e32 v149, v172
	v_mfma_f32_16x16x32_bf16 v[8:11], v[92:95], v[104:107], v[8:11]
	v_mfma_f32_16x16x32_bf16 v[4:7], v[84:87], v[104:107], v[4:7]
	v_mfma_f32_16x16x32_bf16 v[0:3], v[76:79], v[104:107], v[0:3]
	v_mfma_f32_16x16x32_bf16 v[64:67], v[88:91], v[204:207], v[64:67]
	v_mfma_f32_16x16x32_bf16 v[60:63], v[80:83], v[204:207], v[60:63]
	s_waitcnt lgkmcnt(0)
	v_mfma_f32_16x16x32_bf16 v[16:19], v[72:75], v[204:207], v[16:19]
	v_mfma_f32_16x16x32_bf16 v[12:15], v[96:99], v[108:111], v[12:15]
	v_mfma_f32_16x16x32_bf16 v[8:11], v[88:91], v[108:111], v[8:11]
	v_mfma_f32_16x16x32_bf16 v[4:7], v[80:83], v[108:111], v[4:7]
	v_mfma_f32_16x16x32_bf16 v[0:3], v[72:75], v[108:111], v[0:3]

.LBB0_811:
	s_or_b64 exec, exec, s[6:7]
	s_add_i32 s6, s87, 7
	v_min_u32_e32 v44, s6, v166
	v_lshl_add_u32 v73, v44, 6, v201
	v_add_u32_e32 v44, v73, v122
	v_add_u32_e32 v46, v73, v126
	v_max_i32_e32 v172, 0, v44
	v_max_i32_e32 v46, 0, v46
	v_lshl_add_u64 v[44:45], v[134:135], 0, v[172:173]
	v_lshlrev_b32_e32 v172, 1, v46
	v_add_u32_e32 v73, v73, v154
	v_lshlrev_b64 v[44:45], 11, v[44:45]
	v_lshl_add_u64 v[48:49], v[144:145], 0, v[172:173]
	v_max_i32_e32 v172, 0, v73
	v_lshl_add_u64 v[44:45], v[146:147], 0, v[44:45]
	v_lshl_add_u64 v[74:75], v[172:173], 2, v[140:141]
	s_waitcnt lgkmcnt(0)
	s_barrier
	global_load_dwordx4 v[44:47], v[44:45], off
	s_nop 0
	global_load_dwordx4 v[48:51], v[48:49], off
	s_add_i32 s6, s87, 4
	global_load_dword v167, v[74:75], off
	v_cmp_ge_u32_e64 s[6:7], s6, v165
	s_and_saveexec_b64 s[8:9], s[6:7]
	s_xor_b64 s[64:65], exec, s[8:9]
	s_cbranch_execz .LBB0_815
	v_add_u32_e32 v73, s84, v168
	v_add_u32_e32 v73, 0xfffff900, v73
	v_cmp_ge_i32_e64 s[6:7], s93, v73
	s_and_saveexec_b64 s[72:73], s[6:7]
	s_cbranch_execz .LBB0_814
	s_add_i32 s101, s87, 4
	v_readfirstlane_b32 s100, v165
	s_sub_i32 s100, s101, s100
	s_lshl_b32 s100, s100, 6
	s_add_i32 s100, s100, 63
	v_readfirstlane_b32 s101, v192
	s_lshr_b32 s101, s101, 6
	s_lshl_b32 s101, s101, 5
	s_cmp_le_i32 s100, s101
	s_cbranch_scc0 .Lattn_band2
	s_mov_b64 s[6:7], exec
	s_branch .Lattn_nb2
.Lattn_band2:
	v_lshlrev_b32_e32 v73, 1, v159
	v_lshlrev_b32_e32 v74, 1, v157
	v_lshl_add_u32 v108, v158, 2, v72
	v_add3_u32 v171, v72, v73, v74
	ds_read_b128 v[72:75], v171
	ds_read_b128 v[76:79], v171 offset:64
	ds_read_b128 v[80:83], v108 offset:18432
	ds_read_b128 v[84:87], v171 offset:2304
	ds_read_b128 v[88:91], v171 offset:2368
	ds_read_b128 v[92:95], v108 offset:18496
	ds_read_b128 v[96:99], v171 offset:4608
	ds_read_b128 v[100:103], v171 offset:4672
	ds_read_b128 v[104:107], v108 offset:18560
	ds_read_b128 v[150:153], v171 offset:6912
	ds_read_b128 v[188:191], v171 offset:6976
	ds_read_b128 v[204:207], v108 offset:18624
	s_waitcnt lgkmcnt(9)
	v_mfma_f32_16x16x32_bf16 v[108:111], v[72:75], v[20:23], v[80:83]
	s_add_i32 s6, s84, 0x100
	s_cmpk_lt_u32 s6, 0xf0
	s_cselect_b64 s[76:77], -1, 0
	v_mfma_f32_16x16x32_bf16 v[208:211], v[76:79], v[24:27], v[108:111]
	s_waitcnt lgkmcnt(6)
	v_mfma_f32_16x16x32_bf16 v[108:111], v[84:87], v[20:23], v[92:95]
	v_mfma_f32_16x16x32_bf16 v[72:75], v[72:75], v[28:31], v[80:83]
	v_mfma_f32_16x16x32_bf16 v[212:215], v[88:91], v[24:27], v[108:111]
	s_waitcnt lgkmcnt(3)
	v_mfma_f32_16x16x32_bf16 v[108:111], v[96:99], v[20:23], v[104:107]
	v_mfma_f32_16x16x32_bf16 v[116:119], v[76:79], v[32:35], v[72:75]
	v_mfma_f32_16x16x32_bf16 v[72:75], v[84:87], v[28:31], v[92:95]
	v_mfma_f32_16x16x32_bf16 v[216:219], v[100:103], v[24:27], v[108:111]
	s_waitcnt lgkmcnt(0)
	v_mfma_f32_16x16x32_bf16 v[108:111], v[150:153], v[20:23], v[204:207]
	v_mfma_f32_16x16x32_bf16 v[112:115], v[88:91], v[32:35], v[72:75]
	v_mfma_f32_16x16x32_bf16 v[72:75], v[96:99], v[28:31], v[104:107]
	v_mfma_f32_16x16x32_bf16 v[220:223], v[188:191], v[24:27], v[108:111]
	v_mfma_f32_16x16x32_bf16 v[108:111], v[100:103], v[32:35], v[72:75]
	v_mfma_f32_16x16x32_bf16 v[72:75], v[150:153], v[28:31], v[204:207]
	v_add_u32_e32 v150, s84, v158
	v_add_u32_e32 v172, 0x100, v150
	v_cmp_gt_i32_e64 s[6:7], v172, v133
	s_or_b64 s[8:9], s[76:77], s[6:7]
	v_cndmask_b32_e64 v151, v208, v202, s[8:9]
	v_cmp_ge_i32_e64 s[8:9], v172, v133
	s_or_b64 s[8:9], s[76:77], s[8:9]
	v_add_u32_e32 v203, 0x102, v150
	v_cndmask_b32_e64 v152, v209, v202, s[8:9]
	v_cmp_gt_i32_e64 s[8:9], v203, v133
	s_or_b64 s[8:9], s[76:77], s[8:9]
	v_add_u32_e32 v224, 0x103, v150
	v_cndmask_b32_e64 v153, v210, v202, s[8:9]
	v_cmp_gt_i32_e64 s[8:9], v224, v133
	v_mfma_f32_16x16x32_bf16 v[104:107], v[188:191], v[32:35], v[72:75]
	s_or_b64 s[8:9], s[76:77], s[8:9]
	v_cndmask_b32_e64 v177, v211, v202, s[8:9]
	s_nop 0
	v_add_u32_e32 v72, v171, v162
	v_add_u32_e32 v171, 0x110, v150
	v_cmp_gt_u32_e64 s[8:9], s50, v171
	v_cmp_gt_i32_e64 s[10:11], v171, v133
	s_or_b64 s[10:11], s[8:9], s[10:11]
	v_max_f32_e32 v171, v151, v151
	v_cndmask_b32_e64 v180, v212, v202, s[10:11]
	v_add_u32_e32 v212, 0x111, v150
	v_cmp_gt_u32_e64 s[10:11], s50, v212
	v_cmp_gt_i32_e64 s[12:13], v212, v133
	s_or_b64 s[12:13], s[10:11], s[12:13]
	s_or_b64 s[6:7], s[8:9], s[6:7]
	v_cndmask_b32_e64 v181, v213, v202, s[12:13]
	v_add_u32_e32 v213, 0x112, v150
	v_cmp_gt_u32_e64 s[12:13], s50, v213
	v_cmp_gt_i32_e64 s[14:15], v213, v133
	s_or_b64 s[14:15], s[12:13], s[14:15]
	v_cndmask_b32_e64 v112, v112, v202, s[6:7]
	v_cndmask_b32_e64 v182, v214, v202, s[14:15]
	v_add_u32_e32 v214, 0x113, v150
	v_cmp_gt_u32_e64 s[14:15], s50, v214
	v_cmp_gt_i32_e64 s[16:17], v214, v133
	s_or_b64 s[16:17], s[14:15], s[16:17]
	v_cmp_gt_i32_e64 s[6:7], v212, v143
	v_cndmask_b32_e64 v183, v215, v202, s[16:17]
	v_add_u32_e32 v215, 0x120, v150
	v_cmp_gt_u32_e64 s[16:17], s50, v215
	v_cmp_gt_i32_e64 s[18:19], v215, v133
	s_or_b64 s[18:19], s[16:17], s[18:19]
	s_or_b64 s[6:7], s[10:11], s[6:7]
	v_cndmask_b32_e64 v188, v216, v202, s[18:19]
	v_add_u32_e32 v216, 0x121, v150
	v_cmp_gt_u32_e64 s[18:19], s50, v216
	v_cmp_gt_i32_e64 s[20:21], v216, v133
	s_or_b64 s[20:21], s[18:19], s[20:21]
	v_cndmask_b32_e64 v113, v113, v202, s[6:7]
	v_cndmask_b32_e64 v189, v217, v202, s[20:21]
	v_add_u32_e32 v217, 0x122, v150
	v_cmp_gt_u32_e64 s[20:21], s50, v217
	v_cmp_gt_i32_e64 s[22:23], v217, v133
	s_or_b64 s[22:23], s[20:21], s[22:23]
	v_cmp_gt_i32_e64 s[6:7], v213, v143
	v_cndmask_b32_e64 v190, v218, v202, s[22:23]
	v_add_u32_e32 v218, 0x123, v150
	v_cmp_gt_u32_e64 s[22:23], s50, v218
	v_cmp_gt_i32_e64 s[24:25], v218, v133
	s_or_b64 s[24:25], s[22:23], s[24:25]
	s_or_b64 s[6:7], s[12:13], s[6:7]
	v_cndmask_b32_e64 v191, v219, v202, s[24:25]
	v_add_u32_e32 v219, 0x130, v150
	v_cmp_gt_u32_e64 s[24:25], s50, v219
	v_cmp_gt_i32_e64 s[26:27], v219, v133
	s_or_b64 s[26:27], s[24:25], s[26:27]
	v_cndmask_b32_e64 v114, v114, v202, s[6:7]
	v_cndmask_b32_e64 v208, v220, v202, s[26:27]
	v_add_u32_e32 v220, 0x131, v150
	v_cmp_gt_u32_e64 s[26:27], s50, v220
	v_cmp_gt_i32_e64 s[28:29], v220, v133
	s_or_b64 s[28:29], s[26:27], s[28:29]
	v_cmp_gt_i32_e64 s[6:7], v214, v143
	v_cndmask_b32_e64 v209, v221, v202, s[28:29]
	v_add_u32_e32 v221, 0x132, v150
	v_cmp_gt_u32_e64 s[28:29], s50, v221
	v_cmp_gt_i32_e64 s[30:31], v221, v133
	s_or_b64 s[30:31], s[28:29], s[30:31]
	s_or_b64 s[6:7], s[14:15], s[6:7]
	v_cndmask_b32_e64 v210, v222, v202, s[30:31]
	v_add_u32_e32 v222, 0x133, v150
	v_max_f32_e32 v150, v152, v152
	v_max_f32_e32 v150, v171, v150
	v_max3_f32 v150, v150, v153, v177
	v_max3_f32 v150, v150, v180, v181
	v_max3_f32 v150, v150, v182, v183
	v_cmp_gt_u32_e64 s[30:31], s50, v222
	v_cmp_gt_i32_e64 s[36:37], v222, v133
	v_max3_f32 v150, v150, v188, v189
	s_or_b64 s[36:37], s[30:31], s[36:37]
	v_max3_f32 v150, v150, v190, v191
	v_cndmask_b32_e64 v211, v223, v202, s[36:37]
	v_max3_f32 v150, v150, v208, v209
	v_max3_f32 v150, v150, v210, v211
	v_mov_b32_e32 v171, v150
	s_nop 1
	v_permlane16_swap_b32_e32 v150, v171
	v_mov_b32_e32 v171, v150
	s_nop 1
	v_permlane32_swap_b32_e32 v150, v171
	v_max_f32_e32 v150, v150, v150
	v_max_f32_e32 v171, v148, v148
	v_max_f32_e32 v171, v171, v150
	v_sub_f32_e32 v188, v188, v171
	v_sub_f32_e32 v150, v151, v171
	v_exp_f32_e32 v204, v188
	v_sub_f32_e32 v188, v189, v171
	v_exp_f32_e32 v174, v150
	v_sub_f32_e32 v150, v152, v171
	v_exp_f32_e32 v205, v188
	v_sub_f32_e32 v188, v190, v171
	v_exp_f32_e32 v175, v150
	v_sub_f32_e32 v150, v153, v171
	v_sub_f32_e32 v180, v180, v171
	v_sub_f32_e32 v181, v181, v171
	v_exp_f32_e32 v206, v188
	v_sub_f32_e32 v188, v191, v171
	v_exp_f32_e32 v176, v150
	v_sub_f32_e32 v150, v177, v171
	v_exp_f32_e32 v180, v180
	v_exp_f32_e32 v181, v181
	v_exp_f32_e32 v207, v188
	v_sub_f32_e32 v188, v208, v171
	v_exp_f32_e32 v177, v150
	v_sub_f32_e32 v182, v182, v171
	v_sub_f32_e32 v183, v183, v171
	v_exp_f32_e32 v208, v188
	v_sub_f32_e32 v188, v209, v171
	v_exp_f32_e32 v182, v182
	v_exp_f32_e32 v183, v183
	v_exp_f32_e32 v209, v188
	v_sub_f32_e32 v188, v210, v171
	v_pk_add_f32 v[150:151], v[174:175], 0 op_sel_hi:[1,0]
	v_exp_f32_e32 v210, v188
	v_sub_f32_e32 v188, v211, v171
	v_pk_add_f32 v[150:151], v[180:181], v[150:151]
	v_exp_f32_e32 v211, v188
	v_pk_add_f32 v[152:153], v[176:177], 0 op_sel_hi:[1,0]
	v_pk_add_f32 v[150:151], v[204:205], v[150:151]
	v_cndmask_b32_e64 v115, v115, v202, s[6:7]
	v_cmp_gt_i32_e64 s[6:7], v215, v143
	v_pk_add_f32 v[152:153], v[182:183], v[152:153]
	v_pk_add_f32 v[150:151], v[208:209], v[150:151]
	s_or_b64 s[6:7], s[16:17], s[6:7]
	v_pk_add_f32 v[152:153], v[206:207], v[152:153]
	v_add_f32_e32 v150, v150, v151
	v_cndmask_b32_e64 v151, v108, v202, s[6:7]
	v_cmp_gt_i32_e64 s[6:7], v216, v143
	v_pk_add_f32 v[152:153], v[210:211], v[152:153]
	s_or_b64 s[6:7], s[18:19], s[6:7]
	v_add_f32_e32 v152, v152, v153
	v_cmp_gt_i32_e64 s[36:37], v172, v143
	v_cndmask_b32_e64 v153, v109, v202, s[6:7]
	v_cmp_gt_i32_e64 s[6:7], v217, v143
	v_add_u32_e32 v73, 0x2000, v72
	s_or_b64 s[36:37], s[76:77], s[36:37]
	s_or_b64 s[6:7], s[20:21], s[6:7]
	ds_read2_b64 v[100:103], v73 offset0:128 offset1:132
	ds_read2_b64 v[96:99], v73 offset0:136 offset1:140
	v_add_u32_e32 v73, 0x2800, v72
	v_cndmask_b32_e64 v116, v116, v202, s[36:37]
	v_cmp_ge_i32_e64 s[36:37], v172, v143
	v_cndmask_b32_e64 v172, v110, v202, s[6:7]
	v_cmp_gt_i32_e64 s[6:7], v218, v143
	ds_read2_b64 v[92:95], v73 offset0:160 offset1:164
	ds_read2_b64 v[88:91], v73 offset0:168 offset1:172
	v_add_u32_e32 v73, 0x3000, v72
	v_add_u32_e32 v72, 0x3800, v72
	s_or_b64 s[6:7], s[22:23], s[6:7]
	ds_read2_b64 v[84:87], v73 offset0:192 offset1:196
	ds_read2_b64 v[80:83], v73 offset0:200 offset1:204
	ds_read2_b64 v[76:79], v72 offset0:224 offset1:228
	ds_read2_b64 v[72:75], v72 offset0:232 offset1:236
	v_cvt_pk_bf16_f32 v188, v174, v175
	s_or_b64 s[36:37], s[76:77], s[36:37]
	v_cndmask_b32_e64 v174, v111, v202, s[6:7]
	v_cmp_gt_i32_e64 s[6:7], v219, v143
	v_cndmask_b32_e64 v117, v117, v202, s[36:37]
	v_cmp_gt_i32_e64 s[36:37], v203, v143
	s_or_b64 s[6:7], s[24:25], s[6:7]
	s_or_b64 s[36:37], s[76:77], s[36:37]
	v_cndmask_b32_e64 v175, v104, v202, s[6:7]
	v_cmp_gt_i32_e64 s[6:7], v220, v143
	v_cndmask_b32_e64 v118, v118, v202, s[36:37]
	v_cmp_gt_i32_e64 s[36:37], v224, v143
	s_or_b64 s[6:7], s[26:27], s[6:7]
	v_cvt_pk_bf16_f32 v189, v176, v177
	s_or_b64 s[36:37], s[76:77], s[36:37]
	v_cndmask_b32_e64 v176, v105, v202, s[6:7]
	v_max_f32_e32 v104, v117, v117
	v_max_f32_e32 v105, v116, v116
	v_cndmask_b32_e64 v119, v119, v202, s[36:37]
	v_max_f32_e32 v104, v105, v104
	v_max3_f32 v104, v104, v118, v119
	v_cmp_gt_i32_e64 s[6:7], v221, v143
	v_max3_f32 v104, v104, v112, v113
	s_or_b64 s[6:7], s[28:29], s[6:7]
	v_max3_f32 v104, v104, v114, v115
	v_cndmask_b32_e64 v177, v106, v202, s[6:7]
	v_cmp_gt_i32_e64 s[6:7], v222, v143
	v_max3_f32 v104, v104, v151, v153
	s_or_b64 s[6:7], s[30:31], s[6:7]
	v_max3_f32 v104, v104, v172, v174
	v_cvt_pk_bf16_f32 v190, v180, v181
	v_cndmask_b32_e64 v180, v107, v202, s[6:7]
	v_max3_f32 v104, v104, v175, v176
	v_max3_f32 v104, v104, v177, v180
	v_mov_b32_e32 v105, v104
	s_nop 1
	v_permlane16_swap_b32_e32 v104, v105
	v_mov_b32_e32 v105, v104
	s_nop 1
	v_permlane32_swap_b32_e32 v104, v105
	v_max_f32_e32 v104, v104, v104
	v_max_f32_e32 v105, v149, v149
	v_cvt_pk_bf16_f32 v191, v182, v183
	v_max_f32_e32 v182, v105, v104
	v_sub_f32_e32 v104, v116, v182
	v_sub_f32_e32 v105, v117, v182
	v_sub_f32_e32 v106, v118, v182
	v_sub_f32_e32 v107, v119, v182
	v_sub_f32_e32 v116, v151, v182
	v_sub_f32_e32 v151, v175, v182
	v_exp_f32_e32 v104, v104
	v_exp_f32_e32 v105, v105
	v_exp_f32_e32 v106, v106
	v_exp_f32_e32 v107, v107
	v_sub_f32_e32 v112, v112, v182
	v_sub_f32_e32 v113, v113, v182
	v_sub_f32_e32 v114, v114, v182
	v_sub_f32_e32 v115, v115, v182
	v_sub_f32_e32 v119, v174, v182
	v_exp_f32_e32 v174, v151
	v_sub_f32_e32 v151, v176, v182
	v_exp_f32_e32 v112, v112
	v_exp_f32_e32 v113, v113
	v_exp_f32_e32 v114, v114
	v_exp_f32_e32 v115, v115
	v_sub_f32_e32 v117, v153, v182
	v_sub_f32_e32 v118, v172, v182
	v_exp_f32_e32 v175, v151
	v_sub_f32_e32 v151, v177, v182
	v_sub_f32_e32 v148, v148, v171
	v_exp_f32_e32 v116, v116
	v_exp_f32_e32 v117, v117
	v_exp_f32_e32 v118, v118
	v_exp_f32_e32 v119, v119
	v_exp_f32_e32 v176, v151
	v_sub_f32_e32 v151, v180, v182
	v_exp_f32_e32 v148, v148
	v_exp_f32_e32 v177, v151
	v_pk_add_f32 v[108:109], v[104:105], 0 op_sel_hi:[1,0]
	v_pk_add_f32 v[110:111], v[106:107], 0 op_sel_hi:[1,0]
	v_pk_add_f32 v[108:109], v[112:113], v[108:109]
	v_pk_add_f32 v[110:111], v[114:115], v[110:111]
	v_pk_add_f32 v[108:109], v[116:117], v[108:109]
	v_pk_add_f32 v[110:111], v[118:119], v[110:111]
	v_pk_mul_f32 v[70:71], v[70:71], v[148:149] op_sel_hi:[1,0]
	v_pk_mul_f32 v[68:69], v[68:69], v[148:149] op_sel_hi:[1,0]
	v_pk_mul_f32 v[66:67], v[66:67], v[148:149] op_sel_hi:[1,0]
	v_pk_mul_f32 v[64:65], v[64:65], v[148:149] op_sel_hi:[1,0]
	v_pk_mul_f32 v[62:63], v[62:63], v[148:149] op_sel_hi:[1,0]
	v_pk_mul_f32 v[60:61], v[60:61], v[148:149] op_sel_hi:[1,0]
	v_pk_mul_f32 v[18:19], v[18:19], v[148:149] op_sel_hi:[1,0]
	v_pk_mul_f32 v[16:17], v[16:17], v[148:149] op_sel_hi:[1,0]
	v_sub_f32_e32 v149, v149, v182
	v_pk_add_f32 v[110:111], v[176:177], v[110:111]
	v_pk_add_f32 v[108:109], v[174:175], v[108:109]
	v_exp_f32_e32 v149, v149
	v_pk_mov_b32 v[180:181], v[108:109], v[110:111] op_sel:[1,0]
	v_mov_b32_e32 v109, v111
	v_pk_add_f32 v[108:109], v[180:181], v[108:109]
	v_cvt_pk_bf16_f32 v204, v204, v205
	v_cvt_pk_bf16_f32 v205, v206, v207
	v_cvt_pk_bf16_f32 v206, v208, v209
	v_cvt_pk_bf16_f32 v207, v210, v211
	s_waitcnt lgkmcnt(7)
	v_mfma_f32_16x16x32_bf16 v[68:71], v[100:103], v[188:191], v[68:71]
	v_mov_b32_e32 v151, v108
	v_mov_b32_e32 v153, v109
	v_pk_add_f32 v[108:109], v[150:151], v[152:153]
	s_waitcnt lgkmcnt(5)
	v_mfma_f32_16x16x32_bf16 v[64:67], v[92:95], v[188:191], v[64:67]
	v_fma_f32 v136, v136, v148, v108
	v_fma_f32 v137, v137, v149, v109
	v_mov_b32_e32 v108, v149
	v_pk_mul_f32 v[14:15], v[14:15], v[108:109] op_sel_hi:[1,0]
	v_pk_mul_f32 v[12:13], v[12:13], v[108:109] op_sel_hi:[1,0]
	v_pk_mul_f32 v[10:11], v[10:11], v[108:109] op_sel_hi:[1,0]
	v_pk_mul_f32 v[8:9], v[8:9], v[108:109] op_sel_hi:[1,0]
	v_pk_mul_f32 v[6:7], v[6:7], v[108:109] op_sel_hi:[1,0]
	v_pk_mul_f32 v[4:5], v[4:5], v[108:109] op_sel_hi:[1,0]
	v_pk_mul_f32 v[2:3], v[2:3], v[108:109] op_sel_hi:[1,0]
	v_pk_mul_f32 v[0:1], v[0:1], v[108:109] op_sel_hi:[1,0]
	s_waitcnt lgkmcnt(3)
	v_mfma_f32_16x16x32_bf16 v[60:63], v[84:87], v[188:191], v[60:63]
	v_cvt_pk_bf16_f32 v104, v104, v105
	v_cvt_pk_bf16_f32 v105, v106, v107
	v_cvt_pk_bf16_f32 v106, v112, v113
	s_waitcnt lgkmcnt(1)
	v_mfma_f32_16x16x32_bf16 v[16:19], v[76:79], v[188:191], v[16:19]
	v_cvt_pk_bf16_f32 v107, v114, v115
	v_cvt_pk_bf16_f32 v108, v116, v117
	v_cvt_pk_bf16_f32 v109, v118, v119
	v_mfma_f32_16x16x32_bf16 v[68:71], v[96:99], v[204:207], v[68:71]
	v_cvt_pk_bf16_f32 v110, v174, v175
	v_cvt_pk_bf16_f32 v111, v176, v177
	s_mov_b32 s20, s78
	v_mfma_f32_16x16x32_bf16 v[12:15], v[100:103], v[104:107], v[12:15]
	v_mov_b32_e32 v149, v182
	v_mov_b32_e32 v148, v171
	v_mfma_f32_16x16x32_bf16 v[8:11], v[92:95], v[104:107], v[8:11]
	v_mfma_f32_16x16x32_bf16 v[4:7], v[84:87], v[104:107], v[4:7]
	v_mfma_f32_16x16x32_bf16 v[0:3], v[76:79], v[104:107], v[0:3]
	v_mfma_f32_16x16x32_bf16 v[64:67], v[88:91], v[204:207], v[64:67]
	v_mfma_f32_16x16x32_bf16 v[60:63], v[80:83], v[204:207], v[60:63]
	s_waitcnt lgkmcnt(0)
	v_mfma_f32_16x16x32_bf16 v[16:19], v[72:75], v[204:207], v[16:19]
	v_mfma_f32_16x16x32_bf16 v[12:15], v[96:99], v[108:111], v[12:15]
	v_mfma_f32_16x16x32_bf16 v[8:11], v[88:91], v[108:111], v[8:11]
	v_mfma_f32_16x16x32_bf16 v[4:7], v[80:83], v[108:111], v[4:7]
	v_mfma_f32_16x16x32_bf16 v[0:3], v[72:75], v[108:111], v[0:3]

.Lattn_nb2:
	v_lshlrev_b32_e32 v73, 1, v159
	v_lshlrev_b32_e32 v74, 1, v157
	v_lshl_add_u32 v108, v158, 2, v72
	v_add3_u32 v171, v72, v73, v74
	ds_read_b128 v[72:75], v171
	ds_read_b128 v[76:79], v171 offset:64
	ds_read_b128 v[80:83], v108 offset:18432
	ds_read_b128 v[84:87], v171 offset:2304
	ds_read_b128 v[88:91], v171 offset:2368
	ds_read_b128 v[92:95], v108 offset:18496
	ds_read_b128 v[96:99], v171 offset:4608
	ds_read_b128 v[100:103], v171 offset:4672
	ds_read_b128 v[104:107], v108 offset:18560
	ds_read_b128 v[150:153], v171 offset:6912
	ds_read_b128 v[188:191], v171 offset:6976
	ds_read_b128 v[204:207], v108 offset:18624
	s_waitcnt lgkmcnt(9)
	v_mfma_f32_16x16x32_bf16 v[108:111], v[72:75], v[20:23], v[80:83]
	v_mfma_f32_16x16x32_bf16 v[208:211], v[76:79], v[24:27], v[108:111]
	s_waitcnt lgkmcnt(6)
	v_mfma_f32_16x16x32_bf16 v[108:111], v[84:87], v[20:23], v[92:95]
	v_mfma_f32_16x16x32_bf16 v[72:75], v[72:75], v[28:31], v[80:83]
	v_mfma_f32_16x16x32_bf16 v[212:215], v[88:91], v[24:27], v[108:111]
	s_waitcnt lgkmcnt(3)
	v_mfma_f32_16x16x32_bf16 v[108:111], v[96:99], v[20:23], v[104:107]
	v_mfma_f32_16x16x32_bf16 v[116:119], v[76:79], v[32:35], v[72:75]
	v_mfma_f32_16x16x32_bf16 v[72:75], v[84:87], v[28:31], v[92:95]
	v_mfma_f32_16x16x32_bf16 v[216:219], v[100:103], v[24:27], v[108:111]
	s_waitcnt lgkmcnt(0)
	v_mfma_f32_16x16x32_bf16 v[108:111], v[150:153], v[20:23], v[204:207]
	v_mfma_f32_16x16x32_bf16 v[112:115], v[88:91], v[32:35], v[72:75]
	v_mfma_f32_16x16x32_bf16 v[72:75], v[96:99], v[28:31], v[104:107]
	v_mfma_f32_16x16x32_bf16 v[220:223], v[188:191], v[24:27], v[108:111]
	v_mfma_f32_16x16x32_bf16 v[108:111], v[100:103], v[32:35], v[72:75]
	v_mfma_f32_16x16x32_bf16 v[72:75], v[150:153], v[28:31], v[204:207]
	v_max_f32_e32 v150, v209, v209
	v_max_f32_e32 v151, v208, v208
	v_max_f32_e32 v150, v151, v150
	v_max3_f32 v150, v150, v210, v211
	v_max3_f32 v150, v150, v212, v213
	v_max3_f32 v150, v150, v214, v215
	v_max3_f32 v150, v150, v216, v217
	v_max3_f32 v150, v150, v218, v219
	v_max3_f32 v150, v150, v220, v221
	v_max3_f32 v150, v150, v222, v223
	v_mov_b32_e32 v151, v150
	s_nop 1
	v_permlane16_swap_b32_e32 v150, v151
	v_mov_b32_e32 v151, v150
	s_nop 1
	v_permlane32_swap_b32_e32 v150, v151
	v_max_f32_e32 v150, v150, v150
	v_max_f32_e32 v151, v148, v148
	v_mfma_f32_16x16x32_bf16 v[104:107], v[188:191], v[32:35], v[72:75]
	s_nop 2
	v_add_u32_e32 v72, v171, v162
	v_max_f32_e32 v171, v151, v150
	v_sub_f32_e32 v172, v212, v171
	v_exp_f32_e32 v180, v172
	v_sub_f32_e32 v172, v213, v171
	v_exp_f32_e32 v181, v172
	v_sub_f32_e32 v172, v214, v171
	v_exp_f32_e32 v182, v172
	v_sub_f32_e32 v172, v215, v171
	v_exp_f32_e32 v183, v172
	v_sub_f32_e32 v172, v216, v171
	v_sub_f32_e32 v150, v208, v171
	v_exp_f32_e32 v204, v172
	v_sub_f32_e32 v172, v217, v171
	v_exp_f32_e32 v174, v150
	v_sub_f32_e32 v150, v209, v171
	v_exp_f32_e32 v205, v172
	v_sub_f32_e32 v172, v218, v171
	v_exp_f32_e32 v175, v150
	v_sub_f32_e32 v150, v210, v171
	v_exp_f32_e32 v206, v172
	v_sub_f32_e32 v172, v219, v171
	v_exp_f32_e32 v176, v150
	v_sub_f32_e32 v150, v211, v171
	v_exp_f32_e32 v207, v172
	v_sub_f32_e32 v172, v220, v171
	v_exp_f32_e32 v177, v150
	v_exp_f32_e32 v208, v172
	v_sub_f32_e32 v172, v221, v171
	v_exp_f32_e32 v209, v172
	v_sub_f32_e32 v172, v222, v171
	v_exp_f32_e32 v210, v172
	v_sub_f32_e32 v172, v223, v171
	v_exp_f32_e32 v211, v172
	v_pk_add_f32 v[150:151], v[174:175], 0 op_sel_hi:[1,0]
	v_pk_add_f32 v[152:153], v[176:177], 0 op_sel_hi:[1,0]
	v_pk_add_f32 v[150:151], v[180:181], v[150:151]
	v_pk_add_f32 v[152:153], v[182:183], v[152:153]
	v_pk_add_f32 v[150:151], v[204:205], v[150:151]
	v_pk_add_f32 v[152:153], v[206:207], v[152:153]
	v_pk_add_f32 v[150:151], v[208:209], v[150:151]
	v_pk_add_f32 v[152:153], v[210:211], v[152:153]
	v_add_f32_e32 v150, v150, v151
	v_add_f32_e32 v152, v152, v153
	v_max_f32_e32 v151, v117, v117
	v_max_f32_e32 v153, v116, v116
	v_max_f32_e32 v151, v153, v151
	v_max3_f32 v151, v151, v118, v119
	v_max3_f32 v151, v151, v112, v113
	v_max3_f32 v151, v151, v114, v115
	v_max3_f32 v151, v151, v108, v109
	v_max3_f32 v151, v151, v110, v111
	v_max3_f32 v151, v151, v104, v105
	v_max3_f32 v151, v151, v106, v107
	v_mov_b32_e32 v153, v151
	s_nop 1
	v_permlane16_swap_b32_e32 v151, v153
	v_mov_b32_e32 v153, v151
	s_nop 1
	v_permlane32_swap_b32_e32 v151, v153
	v_add_u32_e32 v73, 0x2000, v72
	v_max_f32_e32 v151, v151, v151
	v_max_f32_e32 v153, v149, v149
	ds_read2_b64 v[100:103], v73 offset0:128 offset1:132
	ds_read2_b64 v[96:99], v73 offset0:136 offset1:140
	v_add_u32_e32 v73, 0x2800, v72
	v_max_f32_e32 v172, v153, v151
	ds_read2_b64 v[92:95], v73 offset0:160 offset1:164
	ds_read2_b64 v[88:91], v73 offset0:168 offset1:172
	v_add_u32_e32 v73, 0x3000, v72
	v_add_u32_e32 v72, 0x3800, v72
	v_sub_f32_e32 v116, v116, v172
	v_sub_f32_e32 v117, v117, v172
	v_sub_f32_e32 v118, v118, v172
	v_sub_f32_e32 v119, v119, v172
	v_sub_f32_e32 v104, v104, v172
	ds_read2_b64 v[84:87], v73 offset0:192 offset1:196
	ds_read2_b64 v[80:83], v73 offset0:200 offset1:204
	ds_read2_b64 v[76:79], v72 offset0:224 offset1:228
	ds_read2_b64 v[72:75], v72 offset0:232 offset1:236
	v_cvt_pk_bf16_f32 v188, v174, v175
	v_cvt_pk_bf16_f32 v189, v176, v177
	v_cvt_pk_bf16_f32 v190, v180, v181
	v_exp_f32_e32 v116, v116
	v_exp_f32_e32 v117, v117
	v_exp_f32_e32 v118, v118
	v_exp_f32_e32 v119, v119
	v_sub_f32_e32 v112, v112, v172
	v_sub_f32_e32 v113, v113, v172
	v_sub_f32_e32 v114, v114, v172
	v_sub_f32_e32 v115, v115, v172
	v_exp_f32_e32 v180, v104
	v_sub_f32_e32 v104, v105, v172
	v_exp_f32_e32 v112, v112
	v_exp_f32_e32 v113, v113
	v_exp_f32_e32 v114, v114
	v_exp_f32_e32 v115, v115
	v_sub_f32_e32 v108, v108, v172
	v_sub_f32_e32 v109, v109, v172
	v_sub_f32_e32 v110, v110, v172
	v_sub_f32_e32 v111, v111, v172
	v_exp_f32_e32 v181, v104
	v_sub_f32_e32 v104, v106, v172
	v_sub_f32_e32 v148, v148, v171
	v_cvt_pk_bf16_f32 v191, v182, v183
	v_exp_f32_e32 v108, v108
	v_exp_f32_e32 v109, v109
	v_exp_f32_e32 v110, v110
	v_exp_f32_e32 v111, v111
	v_exp_f32_e32 v182, v104
	v_sub_f32_e32 v104, v107, v172
	v_exp_f32_e32 v148, v148
	v_exp_f32_e32 v183, v104
	v_pk_add_f32 v[174:175], v[116:117], 0 op_sel_hi:[1,0]
	v_pk_add_f32 v[176:177], v[118:119], 0 op_sel_hi:[1,0]
	v_pk_add_f32 v[174:175], v[112:113], v[174:175]
	v_pk_add_f32 v[176:177], v[114:115], v[176:177]
	v_pk_add_f32 v[174:175], v[108:109], v[174:175]
	v_pk_add_f32 v[176:177], v[110:111], v[176:177]
	v_pk_mul_f32 v[70:71], v[70:71], v[148:149] op_sel_hi:[1,0]
	v_pk_mul_f32 v[68:69], v[68:69], v[148:149] op_sel_hi:[1,0]
	v_pk_mul_f32 v[66:67], v[66:67], v[148:149] op_sel_hi:[1,0]
	v_pk_mul_f32 v[64:65], v[64:65], v[148:149] op_sel_hi:[1,0]
	v_pk_mul_f32 v[62:63], v[62:63], v[148:149] op_sel_hi:[1,0]
	v_pk_mul_f32 v[60:61], v[60:61], v[148:149] op_sel_hi:[1,0]
	v_pk_mul_f32 v[18:19], v[18:19], v[148:149] op_sel_hi:[1,0]
	v_pk_mul_f32 v[16:17], v[16:17], v[148:149] op_sel_hi:[1,0]
	v_sub_f32_e32 v149, v149, v172
	v_pk_add_f32 v[104:105], v[182:183], v[176:177]
	v_pk_add_f32 v[106:107], v[180:181], v[174:175]
	v_exp_f32_e32 v149, v149
	v_pk_mov_b32 v[174:175], v[106:107], v[104:105] op_sel:[1,0]
	v_mov_b32_e32 v107, v105
	v_pk_add_f32 v[104:105], v[174:175], v[106:107]
	v_cvt_pk_bf16_f32 v204, v204, v205
	v_cvt_pk_bf16_f32 v205, v206, v207
	v_cvt_pk_bf16_f32 v206, v208, v209
	v_cvt_pk_bf16_f32 v207, v210, v211
	s_waitcnt lgkmcnt(7)
	v_mfma_f32_16x16x32_bf16 v[68:71], v[100:103], v[188:191], v[68:71]
	v_mov_b32_e32 v151, v104
	v_mov_b32_e32 v153, v105
	v_pk_add_f32 v[104:105], v[150:151], v[152:153]
	s_waitcnt lgkmcnt(5)
	v_mfma_f32_16x16x32_bf16 v[64:67], v[92:95], v[188:191], v[64:67]
	v_fma_f32 v136, v136, v148, v104
	v_fma_f32 v137, v137, v149, v105
	v_mov_b32_e32 v104, v149
	v_pk_mul_f32 v[14:15], v[14:15], v[104:105] op_sel_hi:[1,0]
	v_pk_mul_f32 v[12:13], v[12:13], v[104:105] op_sel_hi:[1,0]
	v_pk_mul_f32 v[10:11], v[10:11], v[104:105] op_sel_hi:[1,0]
	v_pk_mul_f32 v[8:9], v[8:9], v[104:105] op_sel_hi:[1,0]
	v_pk_mul_f32 v[6:7], v[6:7], v[104:105] op_sel_hi:[1,0]
	v_pk_mul_f32 v[4:5], v[4:5], v[104:105] op_sel_hi:[1,0]
	v_pk_mul_f32 v[2:3], v[2:3], v[104:105] op_sel_hi:[1,0]
	v_pk_mul_f32 v[0:1], v[0:1], v[104:105] op_sel_hi:[1,0]
	s_waitcnt lgkmcnt(3)
	v_mfma_f32_16x16x32_bf16 v[60:63], v[84:87], v[188:191], v[60:63]
	v_cvt_pk_bf16_f32 v104, v116, v117
	v_cvt_pk_bf16_f32 v105, v118, v119
	v_cvt_pk_bf16_f32 v106, v112, v113
	s_waitcnt lgkmcnt(1)
	v_mfma_f32_16x16x32_bf16 v[16:19], v[76:79], v[188:191], v[16:19]
	v_cvt_pk_bf16_f32 v107, v114, v115
	v_cvt_pk_bf16_f32 v108, v108, v109
	v_cvt_pk_bf16_f32 v109, v110, v111
	v_mfma_f32_16x16x32_bf16 v[68:71], v[96:99], v[204:207], v[68:71]
	v_cvt_pk_bf16_f32 v110, v180, v181
	v_cvt_pk_bf16_f32 v111, v182, v183
	v_mov_b32_e32 v149, v172
	v_mfma_f32_16x16x32_bf16 v[12:15], v[100:103], v[104:107], v[12:15]
	v_mov_b32_e32 v148, v171
	v_mfma_f32_16x16x32_bf16 v[8:11], v[92:95], v[104:107], v[8:11]
	v_mfma_f32_16x16x32_bf16 v[4:7], v[84:87], v[104:107], v[4:7]
	v_mfma_f32_16x16x32_bf16 v[0:3], v[76:79], v[104:107], v[0:3]
	v_mfma_f32_16x16x32_bf16 v[64:67], v[88:91], v[204:207], v[64:67]
	v_mfma_f32_16x16x32_bf16 v[60:63], v[80:83], v[204:207], v[60:63]
	s_waitcnt lgkmcnt(0)
	v_mfma_f32_16x16x32_bf16 v[16:19], v[72:75], v[204:207], v[16:19]
	v_mfma_f32_16x16x32_bf16 v[12:15], v[96:99], v[108:111], v[12:15]
	v_mfma_f32_16x16x32_bf16 v[8:11], v[88:91], v[108:111], v[8:11]
	v_mfma_f32_16x16x32_bf16 v[4:7], v[80:83], v[108:111], v[4:7]
	v_mfma_f32_16x16x32_bf16 v[0:3], v[72:75], v[108:111], v[0:3]

.LBB0_821:
	s_or_b64 exec, exec, s[6:7]
	s_add_i32 s6, s87, 8
	v_min_u32_e32 v52, s6, v166
	v_lshl_add_u32 v73, v52, 6, v201
	v_add_u32_e32 v52, v73, v122
	v_add_u32_e32 v54, v73, v126
	v_max_i32_e32 v172, 0, v52
	v_max_i32_e32 v54, 0, v54
	v_lshl_add_u64 v[52:53], v[134:135], 0, v[172:173]
	v_lshlrev_b32_e32 v172, 1, v54
	v_add_u32_e32 v73, v73, v154
	v_lshlrev_b64 v[52:53], 11, v[52:53]
	v_lshl_add_u64 v[56:57], v[144:145], 0, v[172:173]
	v_max_i32_e32 v172, 0, v73
	v_lshl_add_u64 v[52:53], v[146:147], 0, v[52:53]
	v_lshl_add_u64 v[74:75], v[172:173], 2, v[140:141]
	s_waitcnt lgkmcnt(0)
	s_barrier
	global_load_dwordx4 v[52:55], v[52:53], off
	s_nop 0
	global_load_dwordx4 v[56:59], v[56:57], off
	v_cmp_ge_u32_e64 s[6:7], s8, v165
	global_load_dword v169, v[74:75], off
	s_and_saveexec_b64 s[8:9], s[6:7]
	s_xor_b64 s[64:65], exec, s[8:9]
	s_cbranch_execz .LBB0_825
	v_add_u32_e32 v73, s84, v168
	v_add_u32_e32 v73, 0xfffff940, v73
	v_cmp_ge_i32_e64 s[6:7], s93, v73
	s_and_saveexec_b64 s[72:73], s[6:7]
	s_cbranch_execz .LBB0_824
	s_add_i32 s101, s87, 5
	v_readfirstlane_b32 s100, v165
	s_sub_i32 s100, s101, s100
	s_lshl_b32 s100, s100, 6
	s_add_i32 s100, s100, 63
	v_readfirstlane_b32 s101, v192
	s_lshr_b32 s101, s101, 6
	s_lshl_b32 s101, s101, 5
	s_cmp_le_i32 s100, s101
	s_cbranch_scc0 .Lattn_band3
	s_mov_b64 s[6:7], exec
	s_branch .Lattn_nb3
.Lattn_band3:
	v_lshlrev_b32_e32 v73, 1, v159
	v_lshlrev_b32_e32 v74, 1, v157
	v_lshl_add_u32 v108, v158, 2, v72
	v_add3_u32 v170, v72, v73, v74
	ds_read_b128 v[72:75], v170
	ds_read_b128 v[76:79], v170 offset:64
	ds_read_b128 v[80:83], v108 offset:18432
	ds_read_b128 v[84:87], v170 offset:2304
	ds_read_b128 v[88:91], v170 offset:2368
	ds_read_b128 v[92:95], v108 offset:18496
	ds_read_b128 v[96:99], v170 offset:4608
	ds_read_b128 v[100:103], v170 offset:4672
	ds_read_b128 v[104:107], v108 offset:18560
	ds_read_b128 v[150:153], v170 offset:6912
	ds_read_b128 v[188:191], v170 offset:6976
	ds_read_b128 v[204:207], v108 offset:18624
	s_waitcnt lgkmcnt(9)
	v_mfma_f32_16x16x32_bf16 v[108:111], v[72:75], v[20:23], v[80:83]
	s_add_i32 s6, s84, 0x140
	s_cmpk_lt_u32 s6, 0xf0
	s_cselect_b64 s[76:77], -1, 0
	v_mfma_f32_16x16x32_bf16 v[208:211], v[76:79], v[24:27], v[108:111]
	s_waitcnt lgkmcnt(6)
	v_mfma_f32_16x16x32_bf16 v[108:111], v[84:87], v[20:23], v[92:95]
	v_mfma_f32_16x16x32_bf16 v[72:75], v[72:75], v[28:31], v[80:83]
	v_mfma_f32_16x16x32_bf16 v[212:215], v[88:91], v[24:27], v[108:111]
	s_waitcnt lgkmcnt(3)
	v_mfma_f32_16x16x32_bf16 v[108:111], v[96:99], v[20:23], v[104:107]
	v_mfma_f32_16x16x32_bf16 v[116:119], v[76:79], v[32:35], v[72:75]
	v_mfma_f32_16x16x32_bf16 v[72:75], v[84:87], v[28:31], v[92:95]
	v_mfma_f32_16x16x32_bf16 v[216:219], v[100:103], v[24:27], v[108:111]
	s_waitcnt lgkmcnt(0)
	v_mfma_f32_16x16x32_bf16 v[108:111], v[150:153], v[20:23], v[204:207]
	v_mfma_f32_16x16x32_bf16 v[112:115], v[88:91], v[32:35], v[72:75]
	v_mfma_f32_16x16x32_bf16 v[72:75], v[96:99], v[28:31], v[104:107]
	v_mfma_f32_16x16x32_bf16 v[220:223], v[188:191], v[24:27], v[108:111]
	v_mfma_f32_16x16x32_bf16 v[108:111], v[100:103], v[32:35], v[72:75]
	v_mfma_f32_16x16x32_bf16 v[72:75], v[150:153], v[28:31], v[204:207]
	v_add_u32_e32 v150, s84, v158
	v_add_u32_e32 v172, 0x140, v150
	v_cmp_gt_i32_e64 s[6:7], v172, v133
	s_or_b64 s[8:9], s[76:77], s[6:7]
	v_cndmask_b32_e64 v151, v208, v202, s[8:9]
	v_cmp_ge_i32_e64 s[8:9], v172, v133
	s_or_b64 s[8:9], s[76:77], s[8:9]
	v_add_u32_e32 v203, 0x142, v150
	v_cndmask_b32_e64 v152, v209, v202, s[8:9]
	v_cmp_gt_i32_e64 s[8:9], v203, v133
	s_or_b64 s[8:9], s[76:77], s[8:9]
	v_add_u32_e32 v224, 0x143, v150
	v_cndmask_b32_e64 v153, v210, v202, s[8:9]
	v_cmp_gt_i32_e64 s[8:9], v224, v133
	v_mfma_f32_16x16x32_bf16 v[104:107], v[188:191], v[32:35], v[72:75]
	s_or_b64 s[8:9], s[76:77], s[8:9]
	v_cndmask_b32_e64 v177, v211, v202, s[8:9]
	s_nop 0
	v_add_u32_e32 v72, v170, v162
	v_add_u32_e32 v170, 0x150, v150
	v_cmp_gt_u32_e64 s[8:9], s50, v170
	v_cmp_gt_i32_e64 s[10:11], v170, v133
	s_or_b64 s[10:11], s[8:9], s[10:11]
	v_max_f32_e32 v170, v151, v151
	v_cndmask_b32_e64 v180, v212, v202, s[10:11]
	v_add_u32_e32 v212, 0x151, v150
	v_cmp_gt_u32_e64 s[10:11], s50, v212
	v_cmp_gt_i32_e64 s[12:13], v212, v133
	s_or_b64 s[12:13], s[10:11], s[12:13]
	s_or_b64 s[6:7], s[8:9], s[6:7]
	v_cndmask_b32_e64 v181, v213, v202, s[12:13]
	v_add_u32_e32 v213, 0x152, v150
	v_cmp_gt_u32_e64 s[12:13], s50, v213
	v_cmp_gt_i32_e64 s[14:15], v213, v133
	s_or_b64 s[14:15], s[12:13], s[14:15]
	v_cndmask_b32_e64 v112, v112, v202, s[6:7]
	v_cndmask_b32_e64 v182, v214, v202, s[14:15]
	v_add_u32_e32 v214, 0x153, v150
	v_cmp_gt_u32_e64 s[14:15], s50, v214
	v_cmp_gt_i32_e64 s[16:17], v214, v133
	s_or_b64 s[16:17], s[14:15], s[16:17]
	v_cmp_gt_i32_e64 s[6:7], v212, v143
	v_cndmask_b32_e64 v183, v215, v202, s[16:17]
	v_add_u32_e32 v215, 0x160, v150
	v_cmp_gt_u32_e64 s[16:17], s50, v215
	v_cmp_gt_i32_e64 s[18:19], v215, v133
	s_or_b64 s[18:19], s[16:17], s[18:19]
	s_or_b64 s[6:7], s[10:11], s[6:7]
	v_cndmask_b32_e64 v188, v216, v202, s[18:19]
	v_add_u32_e32 v216, 0x161, v150
	v_cmp_gt_u32_e64 s[18:19], s50, v216
	v_cmp_gt_i32_e64 s[20:21], v216, v133
	s_or_b64 s[20:21], s[18:19], s[20:21]
	v_cndmask_b32_e64 v113, v113, v202, s[6:7]
	v_cndmask_b32_e64 v189, v217, v202, s[20:21]
	v_add_u32_e32 v217, 0x162, v150
	v_cmp_gt_u32_e64 s[20:21], s50, v217
	v_cmp_gt_i32_e64 s[22:23], v217, v133
	s_or_b64 s[22:23], s[20:21], s[22:23]
	v_cmp_gt_i32_e64 s[6:7], v213, v143
	v_cndmask_b32_e64 v190, v218, v202, s[22:23]
	v_add_u32_e32 v218, 0x163, v150
	v_cmp_gt_u32_e64 s[22:23], s50, v218
	v_cmp_gt_i32_e64 s[24:25], v218, v133
	s_or_b64 s[24:25], s[22:23], s[24:25]
	s_or_b64 s[6:7], s[12:13], s[6:7]
	v_cndmask_b32_e64 v191, v219, v202, s[24:25]
	v_add_u32_e32 v219, 0x170, v150
	v_cmp_gt_u32_e64 s[24:25], s50, v219
	v_cmp_gt_i32_e64 s[26:27], v219, v133
	s_or_b64 s[26:27], s[24:25], s[26:27]
	v_cndmask_b32_e64 v114, v114, v202, s[6:7]
	v_cndmask_b32_e64 v208, v220, v202, s[26:27]
	v_add_u32_e32 v220, 0x171, v150
	v_cmp_gt_u32_e64 s[26:27], s50, v220
	v_cmp_gt_i32_e64 s[28:29], v220, v133
	s_or_b64 s[28:29], s[26:27], s[28:29]
	v_cmp_gt_i32_e64 s[6:7], v214, v143
	v_cndmask_b32_e64 v209, v221, v202, s[28:29]
	v_add_u32_e32 v221, 0x172, v150
	v_cmp_gt_u32_e64 s[28:29], s50, v221
	v_cmp_gt_i32_e64 s[30:31], v221, v133
	s_or_b64 s[30:31], s[28:29], s[30:31]
	s_or_b64 s[6:7], s[14:15], s[6:7]
	v_cndmask_b32_e64 v210, v222, v202, s[30:31]
	v_add_u32_e32 v222, 0x173, v150
	v_max_f32_e32 v150, v152, v152
	v_max_f32_e32 v150, v170, v150
	v_max3_f32 v150, v150, v153, v177
	v_max3_f32 v150, v150, v180, v181
	v_max3_f32 v150, v150, v182, v183
	v_cmp_gt_u32_e64 s[30:31], s50, v222
	v_cmp_gt_i32_e64 s[36:37], v222, v133
	v_max3_f32 v150, v150, v188, v189
	s_or_b64 s[36:37], s[30:31], s[36:37]
	v_max3_f32 v150, v150, v190, v191
	v_cndmask_b32_e64 v211, v223, v202, s[36:37]
	v_max3_f32 v150, v150, v208, v209
	v_max3_f32 v150, v150, v210, v211
	v_mov_b32_e32 v170, v150
	s_nop 1
	v_permlane16_swap_b32_e32 v150, v170
	v_mov_b32_e32 v170, v150
	s_nop 1
	v_permlane32_swap_b32_e32 v150, v170
	v_max_f32_e32 v150, v150, v150
	v_max_f32_e32 v170, v148, v148
	v_max_f32_e32 v170, v170, v150
	v_sub_f32_e32 v188, v188, v170
	v_sub_f32_e32 v150, v151, v170
	v_exp_f32_e32 v204, v188
	v_sub_f32_e32 v188, v189, v170
	v_exp_f32_e32 v174, v150
	v_sub_f32_e32 v150, v152, v170
	v_exp_f32_e32 v205, v188
	v_sub_f32_e32 v188, v190, v170
	v_exp_f32_e32 v175, v150
	v_sub_f32_e32 v150, v153, v170
	v_sub_f32_e32 v180, v180, v170
	v_sub_f32_e32 v181, v181, v170
	v_exp_f32_e32 v206, v188
	v_sub_f32_e32 v188, v191, v170
	v_exp_f32_e32 v176, v150
	v_sub_f32_e32 v150, v177, v170
	v_exp_f32_e32 v180, v180
	v_exp_f32_e32 v181, v181
	v_exp_f32_e32 v207, v188
	v_sub_f32_e32 v188, v208, v170
	v_exp_f32_e32 v177, v150
	v_sub_f32_e32 v182, v182, v170
	v_sub_f32_e32 v183, v183, v170
	v_exp_f32_e32 v208, v188
	v_sub_f32_e32 v188, v209, v170
	v_exp_f32_e32 v182, v182
	v_exp_f32_e32 v183, v183
	v_exp_f32_e32 v209, v188
	v_sub_f32_e32 v188, v210, v170
	v_pk_add_f32 v[150:151], v[174:175], 0 op_sel_hi:[1,0]
	v_exp_f32_e32 v210, v188
	v_sub_f32_e32 v188, v211, v170
	v_pk_add_f32 v[150:151], v[180:181], v[150:151]
	v_exp_f32_e32 v211, v188
	v_pk_add_f32 v[152:153], v[176:177], 0 op_sel_hi:[1,0]
	v_pk_add_f32 v[150:151], v[204:205], v[150:151]
	v_cndmask_b32_e64 v115, v115, v202, s[6:7]
	v_cmp_gt_i32_e64 s[6:7], v215, v143
	v_pk_add_f32 v[152:153], v[182:183], v[152:153]
	v_pk_add_f32 v[150:151], v[208:209], v[150:151]
	s_or_b64 s[6:7], s[16:17], s[6:7]
	v_pk_add_f32 v[152:153], v[206:207], v[152:153]
	v_add_f32_e32 v150, v150, v151
	v_cndmask_b32_e64 v151, v108, v202, s[6:7]
	v_cmp_gt_i32_e64 s[6:7], v216, v143
	v_pk_add_f32 v[152:153], v[210:211], v[152:153]
	s_or_b64 s[6:7], s[18:19], s[6:7]
	v_add_f32_e32 v152, v152, v153
	v_cmp_gt_i32_e64 s[36:37], v172, v143
	v_cndmask_b32_e64 v153, v109, v202, s[6:7]
	v_cmp_gt_i32_e64 s[6:7], v217, v143
	v_add_u32_e32 v73, 0x2000, v72
	s_or_b64 s[36:37], s[76:77], s[36:37]
	s_or_b64 s[6:7], s[20:21], s[6:7]
	ds_read2_b64 v[100:103], v73 offset0:128 offset1:132
	ds_read2_b64 v[96:99], v73 offset0:136 offset1:140
	v_add_u32_e32 v73, 0x2800, v72
	v_cndmask_b32_e64 v116, v116, v202, s[36:37]
	v_cmp_ge_i32_e64 s[36:37], v172, v143
	v_cndmask_b32_e64 v172, v110, v202, s[6:7]
	v_cmp_gt_i32_e64 s[6:7], v218, v143
	ds_read2_b64 v[92:95], v73 offset0:160 offset1:164
	ds_read2_b64 v[88:91], v73 offset0:168 offset1:172
	v_add_u32_e32 v73, 0x3000, v72
	v_add_u32_e32 v72, 0x3800, v72
	s_or_b64 s[6:7], s[22:23], s[6:7]
	ds_read2_b64 v[84:87], v73 offset0:192 offset1:196
	ds_read2_b64 v[80:83], v73 offset0:200 offset1:204
	ds_read2_b64 v[76:79], v72 offset0:224 offset1:228
	ds_read2_b64 v[72:75], v72 offset0:232 offset1:236
	v_cvt_pk_bf16_f32 v188, v174, v175
	s_or_b64 s[36:37], s[76:77], s[36:37]
	v_cndmask_b32_e64 v174, v111, v202, s[6:7]
	v_cmp_gt_i32_e64 s[6:7], v219, v143
	v_cndmask_b32_e64 v117, v117, v202, s[36:37]
	v_cmp_gt_i32_e64 s[36:37], v203, v143
	s_or_b64 s[6:7], s[24:25], s[6:7]
	s_or_b64 s[36:37], s[76:77], s[36:37]
	v_cndmask_b32_e64 v175, v104, v202, s[6:7]
	v_cmp_gt_i32_e64 s[6:7], v220, v143
	v_cndmask_b32_e64 v118, v118, v202, s[36:37]
	v_cmp_gt_i32_e64 s[36:37], v224, v143
	s_or_b64 s[6:7], s[26:27], s[6:7]
	v_cvt_pk_bf16_f32 v189, v176, v177
	s_or_b64 s[36:37], s[76:77], s[36:37]
	v_cndmask_b32_e64 v176, v105, v202, s[6:7]
	v_max_f32_e32 v104, v117, v117
	v_max_f32_e32 v105, v116, v116
	v_cndmask_b32_e64 v119, v119, v202, s[36:37]
	v_max_f32_e32 v104, v105, v104
	v_max3_f32 v104, v104, v118, v119
	v_cmp_gt_i32_e64 s[6:7], v221, v143
	v_max3_f32 v104, v104, v112, v113
	s_or_b64 s[6:7], s[28:29], s[6:7]
	v_max3_f32 v104, v104, v114, v115
	v_cndmask_b32_e64 v177, v106, v202, s[6:7]
	v_cmp_gt_i32_e64 s[6:7], v222, v143
	v_max3_f32 v104, v104, v151, v153
	s_or_b64 s[6:7], s[30:31], s[6:7]
	v_max3_f32 v104, v104, v172, v174
	v_cvt_pk_bf16_f32 v190, v180, v181
	v_cndmask_b32_e64 v180, v107, v202, s[6:7]
	v_max3_f32 v104, v104, v175, v176
	v_max3_f32 v104, v104, v177, v180
	v_mov_b32_e32 v105, v104
	s_nop 1
	v_permlane16_swap_b32_e32 v104, v105
	v_mov_b32_e32 v105, v104
	s_nop 1
	v_permlane32_swap_b32_e32 v104, v105
	v_max_f32_e32 v104, v104, v104
	v_max_f32_e32 v105, v149, v149
	v_cvt_pk_bf16_f32 v191, v182, v183
	v_max_f32_e32 v182, v105, v104
	v_sub_f32_e32 v104, v116, v182
	v_sub_f32_e32 v105, v117, v182
	v_sub_f32_e32 v106, v118, v182
	v_sub_f32_e32 v107, v119, v182
	v_sub_f32_e32 v116, v151, v182
	v_sub_f32_e32 v151, v175, v182
	v_exp_f32_e32 v104, v104
	v_exp_f32_e32 v105, v105
	v_exp_f32_e32 v106, v106
	v_exp_f32_e32 v107, v107
	v_sub_f32_e32 v112, v112, v182
	v_sub_f32_e32 v113, v113, v182
	v_sub_f32_e32 v114, v114, v182
	v_sub_f32_e32 v115, v115, v182
	v_sub_f32_e32 v119, v174, v182
	v_exp_f32_e32 v174, v151
	v_sub_f32_e32 v151, v176, v182
	v_exp_f32_e32 v112, v112
	v_exp_f32_e32 v113, v113
	v_exp_f32_e32 v114, v114
	v_exp_f32_e32 v115, v115
	v_sub_f32_e32 v117, v153, v182
	v_sub_f32_e32 v118, v172, v182
	v_exp_f32_e32 v175, v151
	v_sub_f32_e32 v151, v177, v182
	v_sub_f32_e32 v148, v148, v170
	v_exp_f32_e32 v116, v116
	v_exp_f32_e32 v117, v117
	v_exp_f32_e32 v118, v118
	v_exp_f32_e32 v119, v119
	v_exp_f32_e32 v176, v151
	v_sub_f32_e32 v151, v180, v182
	v_exp_f32_e32 v148, v148
	v_exp_f32_e32 v177, v151
	v_pk_add_f32 v[108:109], v[104:105], 0 op_sel_hi:[1,0]
	v_pk_add_f32 v[110:111], v[106:107], 0 op_sel_hi:[1,0]
	v_pk_add_f32 v[108:109], v[112:113], v[108:109]
	v_pk_add_f32 v[110:111], v[114:115], v[110:111]
	v_pk_add_f32 v[108:109], v[116:117], v[108:109]
	v_pk_add_f32 v[110:111], v[118:119], v[110:111]
	v_pk_mul_f32 v[70:71], v[70:71], v[148:149] op_sel_hi:[1,0]
	v_pk_mul_f32 v[68:69], v[68:69], v[148:149] op_sel_hi:[1,0]
	v_pk_mul_f32 v[66:67], v[66:67], v[148:149] op_sel_hi:[1,0]
	v_pk_mul_f32 v[64:65], v[64:65], v[148:149] op_sel_hi:[1,0]
	v_pk_mul_f32 v[62:63], v[62:63], v[148:149] op_sel_hi:[1,0]
	v_pk_mul_f32 v[60:61], v[60:61], v[148:149] op_sel_hi:[1,0]
	v_pk_mul_f32 v[18:19], v[18:19], v[148:149] op_sel_hi:[1,0]
	v_pk_mul_f32 v[16:17], v[16:17], v[148:149] op_sel_hi:[1,0]
	v_sub_f32_e32 v149, v149, v182
	v_pk_add_f32 v[110:111], v[176:177], v[110:111]
	v_pk_add_f32 v[108:109], v[174:175], v[108:109]
	v_exp_f32_e32 v149, v149
	v_pk_mov_b32 v[180:181], v[108:109], v[110:111] op_sel:[1,0]
	v_mov_b32_e32 v109, v111
	v_pk_add_f32 v[108:109], v[180:181], v[108:109]
	v_cvt_pk_bf16_f32 v204, v204, v205
	v_cvt_pk_bf16_f32 v205, v206, v207
	v_cvt_pk_bf16_f32 v206, v208, v209
	v_cvt_pk_bf16_f32 v207, v210, v211
	s_waitcnt lgkmcnt(7)
	v_mfma_f32_16x16x32_bf16 v[68:71], v[100:103], v[188:191], v[68:71]
	v_mov_b32_e32 v151, v108
	v_mov_b32_e32 v153, v109
	v_pk_add_f32 v[108:109], v[150:151], v[152:153]
	s_waitcnt lgkmcnt(5)
	v_mfma_f32_16x16x32_bf16 v[64:67], v[92:95], v[188:191], v[64:67]
	v_fma_f32 v136, v136, v148, v108
	v_fma_f32 v137, v137, v149, v109
	v_mov_b32_e32 v108, v149
	v_pk_mul_f32 v[14:15], v[14:15], v[108:109] op_sel_hi:[1,0]
	v_pk_mul_f32 v[12:13], v[12:13], v[108:109] op_sel_hi:[1,0]
	v_pk_mul_f32 v[10:11], v[10:11], v[108:109] op_sel_hi:[1,0]
	v_pk_mul_f32 v[8:9], v[8:9], v[108:109] op_sel_hi:[1,0]
	v_pk_mul_f32 v[6:7], v[6:7], v[108:109] op_sel_hi:[1,0]
	v_pk_mul_f32 v[4:5], v[4:5], v[108:109] op_sel_hi:[1,0]
	v_pk_mul_f32 v[2:3], v[2:3], v[108:109] op_sel_hi:[1,0]
	v_pk_mul_f32 v[0:1], v[0:1], v[108:109] op_sel_hi:[1,0]
	s_waitcnt lgkmcnt(3)
	v_mfma_f32_16x16x32_bf16 v[60:63], v[84:87], v[188:191], v[60:63]
	v_cvt_pk_bf16_f32 v104, v104, v105
	v_cvt_pk_bf16_f32 v105, v106, v107
	v_cvt_pk_bf16_f32 v106, v112, v113
	s_waitcnt lgkmcnt(1)
	v_mfma_f32_16x16x32_bf16 v[16:19], v[76:79], v[188:191], v[16:19]
	v_cvt_pk_bf16_f32 v107, v114, v115
	v_cvt_pk_bf16_f32 v108, v116, v117
	v_cvt_pk_bf16_f32 v109, v118, v119
	v_mfma_f32_16x16x32_bf16 v[68:71], v[96:99], v[204:207], v[68:71]
	v_cvt_pk_bf16_f32 v110, v174, v175
	v_cvt_pk_bf16_f32 v111, v176, v177
	s_mov_b32 s20, s78
	v_mfma_f32_16x16x32_bf16 v[12:15], v[100:103], v[104:107], v[12:15]
	v_mov_b32_e32 v149, v182
	v_mov_b32_e32 v148, v170
	v_mfma_f32_16x16x32_bf16 v[8:11], v[92:95], v[104:107], v[8:11]
	v_mfma_f32_16x16x32_bf16 v[4:7], v[84:87], v[104:107], v[4:7]
	v_mfma_f32_16x16x32_bf16 v[0:3], v[76:79], v[104:107], v[0:3]
	v_mfma_f32_16x16x32_bf16 v[64:67], v[88:91], v[204:207], v[64:67]
	v_mfma_f32_16x16x32_bf16 v[60:63], v[80:83], v[204:207], v[60:63]
	s_waitcnt lgkmcnt(0)
	v_mfma_f32_16x16x32_bf16 v[16:19], v[72:75], v[204:207], v[16:19]
	v_mfma_f32_16x16x32_bf16 v[12:15], v[96:99], v[108:111], v[12:15]
	v_mfma_f32_16x16x32_bf16 v[8:11], v[88:91], v[108:111], v[8:11]
	v_mfma_f32_16x16x32_bf16 v[4:7], v[80:83], v[108:111], v[4:7]
	v_mfma_f32_16x16x32_bf16 v[0:3], v[72:75], v[108:111], v[0:3]

.Lattn_nb3:
	v_lshlrev_b32_e32 v73, 1, v159
	v_lshlrev_b32_e32 v74, 1, v157
	v_lshl_add_u32 v108, v158, 2, v72
	v_add3_u32 v170, v72, v73, v74
	ds_read_b128 v[72:75], v170
	ds_read_b128 v[76:79], v170 offset:64
	ds_read_b128 v[80:83], v108 offset:18432
	ds_read_b128 v[84:87], v170 offset:2304
	ds_read_b128 v[88:91], v170 offset:2368
	ds_read_b128 v[92:95], v108 offset:18496
	ds_read_b128 v[96:99], v170 offset:4608
	ds_read_b128 v[100:103], v170 offset:4672
	ds_read_b128 v[104:107], v108 offset:18560
	ds_read_b128 v[150:153], v170 offset:6912
	ds_read_b128 v[188:191], v170 offset:6976
	ds_read_b128 v[204:207], v108 offset:18624
	s_waitcnt lgkmcnt(9)
	v_mfma_f32_16x16x32_bf16 v[108:111], v[72:75], v[20:23], v[80:83]
	v_mfma_f32_16x16x32_bf16 v[208:211], v[76:79], v[24:27], v[108:111]
	s_waitcnt lgkmcnt(6)
	v_mfma_f32_16x16x32_bf16 v[108:111], v[84:87], v[20:23], v[92:95]
	v_mfma_f32_16x16x32_bf16 v[72:75], v[72:75], v[28:31], v[80:83]
	v_mfma_f32_16x16x32_bf16 v[212:215], v[88:91], v[24:27], v[108:111]
	s_waitcnt lgkmcnt(3)
	v_mfma_f32_16x16x32_bf16 v[108:111], v[96:99], v[20:23], v[104:107]
	v_mfma_f32_16x16x32_bf16 v[116:119], v[76:79], v[32:35], v[72:75]
	v_mfma_f32_16x16x32_bf16 v[72:75], v[84:87], v[28:31], v[92:95]
	v_mfma_f32_16x16x32_bf16 v[216:219], v[100:103], v[24:27], v[108:111]
	s_waitcnt lgkmcnt(0)
	v_mfma_f32_16x16x32_bf16 v[108:111], v[150:153], v[20:23], v[204:207]
	v_mfma_f32_16x16x32_bf16 v[112:115], v[88:91], v[32:35], v[72:75]
	v_mfma_f32_16x16x32_bf16 v[72:75], v[96:99], v[28:31], v[104:107]
	v_mfma_f32_16x16x32_bf16 v[220:223], v[188:191], v[24:27], v[108:111]
	v_mfma_f32_16x16x32_bf16 v[108:111], v[100:103], v[32:35], v[72:75]
	v_mfma_f32_16x16x32_bf16 v[72:75], v[150:153], v[28:31], v[204:207]
	v_max_f32_e32 v150, v209, v209
	v_max_f32_e32 v151, v208, v208
	v_max_f32_e32 v150, v151, v150
	v_max3_f32 v150, v150, v210, v211
	v_max3_f32 v150, v150, v212, v213
	v_max3_f32 v150, v150, v214, v215
	v_max3_f32 v150, v150, v216, v217
	v_max3_f32 v150, v150, v218, v219
	v_max3_f32 v150, v150, v220, v221
	v_max3_f32 v150, v150, v222, v223
	v_mov_b32_e32 v151, v150
	s_nop 1
	v_permlane16_swap_b32_e32 v150, v151
	v_mov_b32_e32 v151, v150
	s_nop 1
	v_permlane32_swap_b32_e32 v150, v151
	v_max_f32_e32 v150, v150, v150
	v_max_f32_e32 v151, v148, v148
	v_mfma_f32_16x16x32_bf16 v[104:107], v[188:191], v[32:35], v[72:75]
	s_nop 2
	v_add_u32_e32 v72, v170, v162
	v_max_f32_e32 v170, v151, v150
	v_sub_f32_e32 v172, v212, v170
	v_exp_f32_e32 v180, v172
	v_sub_f32_e32 v172, v213, v170
	v_exp_f32_e32 v181, v172
	v_sub_f32_e32 v172, v214, v170
	v_exp_f32_e32 v182, v172
	v_sub_f32_e32 v172, v215, v170
	v_exp_f32_e32 v183, v172
	v_sub_f32_e32 v172, v216, v170
	v_sub_f32_e32 v150, v208, v170
	v_exp_f32_e32 v204, v172
	v_sub_f32_e32 v172, v217, v170
	v_exp_f32_e32 v174, v150
	v_sub_f32_e32 v150, v209, v170
	v_exp_f32_e32 v205, v172
	v_sub_f32_e32 v172, v218, v170
	v_exp_f32_e32 v175, v150
	v_sub_f32_e32 v150, v210, v170
	v_exp_f32_e32 v206, v172
	v_sub_f32_e32 v172, v219, v170
	v_exp_f32_e32 v176, v150
	v_sub_f32_e32 v150, v211, v170
	v_exp_f32_e32 v207, v172
	v_sub_f32_e32 v172, v220, v170
	v_exp_f32_e32 v177, v150
	v_exp_f32_e32 v208, v172
	v_sub_f32_e32 v172, v221, v170
	v_exp_f32_e32 v209, v172
	v_sub_f32_e32 v172, v222, v170
	v_exp_f32_e32 v210, v172
	v_sub_f32_e32 v172, v223, v170
	v_exp_f32_e32 v211, v172
	v_pk_add_f32 v[150:151], v[174:175], 0 op_sel_hi:[1,0]
	v_pk_add_f32 v[152:153], v[176:177], 0 op_sel_hi:[1,0]
	v_pk_add_f32 v[150:151], v[180:181], v[150:151]
	v_pk_add_f32 v[152:153], v[182:183], v[152:153]
	v_pk_add_f32 v[150:151], v[204:205], v[150:151]
	v_pk_add_f32 v[152:153], v[206:207], v[152:153]
	v_pk_add_f32 v[150:151], v[208:209], v[150:151]
	v_pk_add_f32 v[152:153], v[210:211], v[152:153]
	v_add_f32_e32 v150, v150, v151
	v_add_f32_e32 v152, v152, v153
	v_max_f32_e32 v151, v117, v117
	v_max_f32_e32 v153, v116, v116
	v_max_f32_e32 v151, v153, v151
	v_max3_f32 v151, v151, v118, v119
	v_max3_f32 v151, v151, v112, v113
	v_max3_f32 v151, v151, v114, v115
	v_max3_f32 v151, v151, v108, v109
	v_max3_f32 v151, v151, v110, v111
	v_max3_f32 v151, v151, v104, v105
	v_max3_f32 v151, v151, v106, v107
	v_mov_b32_e32 v153, v151
	s_nop 1
	v_permlane16_swap_b32_e32 v151, v153
	v_mov_b32_e32 v153, v151
	s_nop 1
	v_permlane32_swap_b32_e32 v151, v153
	v_add_u32_e32 v73, 0x2000, v72
	v_max_f32_e32 v151, v151, v151
	v_max_f32_e32 v153, v149, v149
	ds_read2_b64 v[100:103], v73 offset0:128 offset1:132
	ds_read2_b64 v[96:99], v73 offset0:136 offset1:140
	v_add_u32_e32 v73, 0x2800, v72
	v_max_f32_e32 v172, v153, v151
	ds_read2_b64 v[92:95], v73 offset0:160 offset1:164
	ds_read2_b64 v[88:91], v73 offset0:168 offset1:172
	v_add_u32_e32 v73, 0x3000, v72
	v_add_u32_e32 v72, 0x3800, v72
	v_sub_f32_e32 v116, v116, v172
	v_sub_f32_e32 v117, v117, v172
	v_sub_f32_e32 v118, v118, v172
	v_sub_f32_e32 v119, v119, v172
	v_sub_f32_e32 v104, v104, v172
	ds_read2_b64 v[84:87], v73 offset0:192 offset1:196
	ds_read2_b64 v[80:83], v73 offset0:200 offset1:204
	ds_read2_b64 v[76:79], v72 offset0:224 offset1:228
	ds_read2_b64 v[72:75], v72 offset0:232 offset1:236
	v_cvt_pk_bf16_f32 v188, v174, v175
	v_cvt_pk_bf16_f32 v189, v176, v177
	v_cvt_pk_bf16_f32 v190, v180, v181
	v_exp_f32_e32 v116, v116
	v_exp_f32_e32 v117, v117
	v_exp_f32_e32 v118, v118
	v_exp_f32_e32 v119, v119
	v_sub_f32_e32 v112, v112, v172
	v_sub_f32_e32 v113, v113, v172
	v_sub_f32_e32 v114, v114, v172
	v_sub_f32_e32 v115, v115, v172
	v_exp_f32_e32 v180, v104
	v_sub_f32_e32 v104, v105, v172
	v_exp_f32_e32 v112, v112
	v_exp_f32_e32 v113, v113
	v_exp_f32_e32 v114, v114
	v_exp_f32_e32 v115, v115
	v_sub_f32_e32 v108, v108, v172
	v_sub_f32_e32 v109, v109, v172
	v_sub_f32_e32 v110, v110, v172
	v_sub_f32_e32 v111, v111, v172
	v_exp_f32_e32 v181, v104
	v_sub_f32_e32 v104, v106, v172
	v_sub_f32_e32 v148, v148, v170
	v_cvt_pk_bf16_f32 v191, v182, v183
	v_exp_f32_e32 v108, v108
	v_exp_f32_e32 v109, v109
	v_exp_f32_e32 v110, v110
	v_exp_f32_e32 v111, v111
	v_exp_f32_e32 v182, v104
	v_sub_f32_e32 v104, v107, v172
	v_exp_f32_e32 v148, v148
	v_exp_f32_e32 v183, v104
	v_pk_add_f32 v[174:175], v[116:117], 0 op_sel_hi:[1,0]
	v_pk_add_f32 v[176:177], v[118:119], 0 op_sel_hi:[1,0]
	v_pk_add_f32 v[174:175], v[112:113], v[174:175]
	v_pk_add_f32 v[176:177], v[114:115], v[176:177]
	v_pk_add_f32 v[174:175], v[108:109], v[174:175]
	v_pk_add_f32 v[176:177], v[110:111], v[176:177]
	v_pk_mul_f32 v[70:71], v[70:71], v[148:149] op_sel_hi:[1,0]
	v_pk_mul_f32 v[68:69], v[68:69], v[148:149] op_sel_hi:[1,0]
	v_pk_mul_f32 v[66:67], v[66:67], v[148:149] op_sel_hi:[1,0]
	v_pk_mul_f32 v[64:65], v[64:65], v[148:149] op_sel_hi:[1,0]
	v_pk_mul_f32 v[62:63], v[62:63], v[148:149] op_sel_hi:[1,0]
	v_pk_mul_f32 v[60:61], v[60:61], v[148:149] op_sel_hi:[1,0]
	v_pk_mul_f32 v[18:19], v[18:19], v[148:149] op_sel_hi:[1,0]
	v_pk_mul_f32 v[16:17], v[16:17], v[148:149] op_sel_hi:[1,0]
	v_sub_f32_e32 v149, v149, v172
	v_pk_add_f32 v[104:105], v[182:183], v[176:177]
	v_pk_add_f32 v[106:107], v[180:181], v[174:175]
	v_exp_f32_e32 v149, v149
	v_pk_mov_b32 v[174:175], v[106:107], v[104:105] op_sel:[1,0]
	v_mov_b32_e32 v107, v105
	v_pk_add_f32 v[104:105], v[174:175], v[106:107]
	v_cvt_pk_bf16_f32 v204, v204, v205
	v_cvt_pk_bf16_f32 v205, v206, v207
	v_cvt_pk_bf16_f32 v206, v208, v209
	v_cvt_pk_bf16_f32 v207, v210, v211
	s_waitcnt lgkmcnt(7)
	v_mfma_f32_16x16x32_bf16 v[68:71], v[100:103], v[188:191], v[68:71]
	v_mov_b32_e32 v151, v104
	v_mov_b32_e32 v153, v105
	v_pk_add_f32 v[104:105], v[150:151], v[152:153]
	s_waitcnt lgkmcnt(5)
	v_mfma_f32_16x16x32_bf16 v[64:67], v[92:95], v[188:191], v[64:67]
	v_fma_f32 v136, v136, v148, v104
	v_fma_f32 v137, v137, v149, v105
	v_mov_b32_e32 v104, v149
	v_pk_mul_f32 v[14:15], v[14:15], v[104:105] op_sel_hi:[1,0]
	v_pk_mul_f32 v[12:13], v[12:13], v[104:105] op_sel_hi:[1,0]
	v_pk_mul_f32 v[10:11], v[10:11], v[104:105] op_sel_hi:[1,0]
	v_pk_mul_f32 v[8:9], v[8:9], v[104:105] op_sel_hi:[1,0]
	v_pk_mul_f32 v[6:7], v[6:7], v[104:105] op_sel_hi:[1,0]
	v_pk_mul_f32 v[4:5], v[4:5], v[104:105] op_sel_hi:[1,0]
	v_pk_mul_f32 v[2:3], v[2:3], v[104:105] op_sel_hi:[1,0]
	v_pk_mul_f32 v[0:1], v[0:1], v[104:105] op_sel_hi:[1,0]
	s_waitcnt lgkmcnt(3)
	v_mfma_f32_16x16x32_bf16 v[60:63], v[84:87], v[188:191], v[60:63]
	v_cvt_pk_bf16_f32 v104, v116, v117
	v_cvt_pk_bf16_f32 v105, v118, v119
	v_cvt_pk_bf16_f32 v106, v112, v113
	s_waitcnt lgkmcnt(1)
	v_mfma_f32_16x16x32_bf16 v[16:19], v[76:79], v[188:191], v[16:19]
	v_cvt_pk_bf16_f32 v107, v114, v115
	v_cvt_pk_bf16_f32 v108, v108, v109
	v_cvt_pk_bf16_f32 v109, v110, v111
	v_mfma_f32_16x16x32_bf16 v[68:71], v[96:99], v[204:207], v[68:71]
	v_cvt_pk_bf16_f32 v110, v180, v181
	v_cvt_pk_bf16_f32 v111, v182, v183
	v_mov_b32_e32 v148, v170
	v_mfma_f32_16x16x32_bf16 v[12:15], v[100:103], v[104:107], v[12:15]
	v_mov_b32_e32 v149, v172
	v_mfma_f32_16x16x32_bf16 v[8:11], v[92:95], v[104:107], v[8:11]
	v_mfma_f32_16x16x32_bf16 v[4:7], v[84:87], v[104:107], v[4:7]
	v_mfma_f32_16x16x32_bf16 v[0:3], v[76:79], v[104:107], v[0:3]
	v_mfma_f32_16x16x32_bf16 v[64:67], v[88:91], v[204:207], v[64:67]
	v_mfma_f32_16x16x32_bf16 v[60:63], v[80:83], v[204:207], v[60:63]
	s_waitcnt lgkmcnt(0)
	v_mfma_f32_16x16x32_bf16 v[16:19], v[72:75], v[204:207], v[16:19]
	v_mfma_f32_16x16x32_bf16 v[12:15], v[96:99], v[108:111], v[12:15]
	v_mfma_f32_16x16x32_bf16 v[8:11], v[88:91], v[108:111], v[8:11]
	v_mfma_f32_16x16x32_bf16 v[4:7], v[80:83], v[108:111], v[4:7]
	v_mfma_f32_16x16x32_bf16 v[0:3], v[72:75], v[108:111], v[0:3]
	s_branch .LBB0_796
